# GEMM K-loops hand-off trim: s_setprio 1 moved before each segment-opening barrier, provably no-op lgkmcnt(0) after it deleted, s_setprio 0 moved after each closing barrier (3 fewer issue slots on the
# speedup vs baseline: 1.0076x; 1.0033x over previous
; #define PG8_STAGE(bufoff, gbase, voff) do { _Pragma("unroll") for (int _i = 0; _i < 2; ++_i) \
;         __builtin_amdgcn_global_load_lds((const unsigned*)((const char*)(gbase) + (voff)[_i]), (PG8_LAS unsigned*)(lds + (bufoff) + ldsw + _i * 8192), 16, 0, 0); } while (0)
; #define PG8_LDA(dst, b, h) do { _Pragma("unroll") for (int m = 0; m < 4; ++m) _Pragma("unroll") for (int k = 0; k < 2; ++k) dst[m][k] = *(const PG8_LAS bf16x8*)(lds + PG8_SA(b, h) + aoff + m * 2048 + k * 1024); } while (0)
; #define PG8_LDB(dst, b, h) do { _Pragma("unroll") for (int n = 0; n < 2; ++n) _Pragma("unroll") for (int k = 0; k < 2; ++k) dst[n][k] = *(const PG8_LAS bf16x8*)(lds + PG8_SB(b, h) + boff + n * 2048 + k * 1024); } while (0)
; #define PG8_MMA(ai, bj, At, Bt) do { __builtin_amdgcn_s_setprio(1); _Pragma("unroll") for (int m = 0; m < 4; ++m) _Pragma("unroll") for (int n = 0; n < 2; ++n) _Pragma("unroll") for (int k = 0; k < 2; ++k) \
;         acc[ai][bj][m][n] = __builtin_amdgcn_mfma_f32_16x16x32_bf16(Bt[n][k], At[m][k], acc[ai][bj][m][n], 0, 0, 0); __builtin_amdgcn_s_setprio(0); } while (0)
; #define PG8_WAIT_V(n) asm volatile("s_waitcnt vmcnt(" #n ")" ::: "memory")
; #define PG8_WAIT_L(n) asm volatile("s_waitcnt lgkmcnt(" #n ")" ::: "memory")
; template <class Epi, class Sched, bool ALIGN_EPI = false, bool SP2 = false>
; __device__ __forceinline__ void gemm_phase(PG8_LAS unsigned char* lds, const Gemm g, const Sched& S, const Epi& E) {
;     ...
;             const bool last = (t == nt - 2);
;             const char* a1 = cA + (size_t)(t + 1) * kstep;
;             const char* a2 = last ? nA : cA + (size_t)(t + 2) * kstep; const char* b2 = last ? nB : cB + (size_t)(t + 2) * kstep;
;             const char* a3 = a2 + kstep; const char* b3 = b2 + kstep;
;             if (last && has_next) S.a_ready(nxt);
;             if constexpr (SP2) {
;             PG8_LDB(B0, 0, 0); PG8_LDB(B1, 0, 1); PG8_SCHED; PG8_LDA(At, 0, 0); PG8_STAGE(PG8_SA(1, 1), a1 + hstep, voffA);
;             PG8_WAIT_V(8); PG8_WAIT_L(0); PG8_BAR; PG8_MMA(0, 0, At, B0); PG8_MMA(0, 1, At, B1); PG8_BAR; PG8_SCHED;
;             PG8_LDA(At, 0, 1); PG8_STAGE(PG8_SB(0, 0), b2, voffB); PG8_STAGE(PG8_SB(0, 1), b2 + hstep, voffB); PG8_STAGE(PG8_SA(0, 0), a2, voffA);
;             PG8_WAIT_V(8); PG8_WAIT_L(0); PG8_BAR; PG8_MMA(1, 0, At, B0); PG8_MMA(1, 1, At, B1); PG8_BAR; PG8_SCHED;
.LBB0_183:
	ds_read_b128 v[144:147], v186
	ds_read_b128 v[148:151], v186 offset:1024
	ds_read_b128 v[152:155], v186 offset:2048
	ds_read_b128 v[156:159], v186 offset:3072
	ds_read_b128 v[160:163], v187
	ds_read_b128 v[164:167], v187 offset:1024
	ds_read_b128 v[168:171], v187 offset:2048
	ds_read_b128 v[172:175], v187 offset:3072
	s_add_u32 s8, s6, 0xfff00080
	s_addc_u32 s9, s7, -1
	s_cmp_eq_u32 s17, 60
	s_cselect_b32 s11, s1, s9
	s_cselect_b32 s10, s12, s8
	s_cselect_b32 s9, s13, s16
	s_cselect_b32 s8, s14, s15
	v_lshl_add_u64 v[214:215], s[6:7], 0, v[140:141]
	s_add_i32 m0, s41, 0xc000
	s_waitcnt lgkmcnt(0)
	ds_read_b128 v[176:179], v188
	ds_read_b128 v[190:193], v188 offset:1024
	ds_read_b128 v[194:197], v188 offset:2048
	ds_read_b128 v[198:201], v188 offset:3072
	ds_read_b128 v[202:205], v188 offset:4096
	ds_read_b128 v[206:209], v188 offset:5120
	ds_read_b128 v[210:213], v188 offset:6144
	ds_read_b128 v[218:221], v188 offset:7168
	global_load_lds_dwordx4 v[214:215], off
	v_lshl_add_u64 v[214:215], s[6:7], 0, v[142:143]
	s_add_i32 m0, s41, 0xe000
	s_nop 0
	global_load_lds_dwordx4 v[214:215], off
	s_waitcnt vmcnt(8)
	s_waitcnt lgkmcnt(0)
	s_setprio 1
	s_barrier
	v_mfma_f32_16x16x32_bf16 v[126:129], v[144:147], v[176:179], v[126:129]
	v_mfma_f32_16x16x32_bf16 v[122:125], v[152:155], v[176:179], v[122:125]
	v_mfma_f32_16x16x32_bf16 v[114:117], v[144:147], v[194:197], v[114:117]
	v_mfma_f32_16x16x32_bf16 v[106:109], v[152:155], v[194:197], v[106:109]
	v_mfma_f32_16x16x32_bf16 v[98:101], v[144:147], v[202:205], v[98:101]
	v_mfma_f32_16x16x32_bf16 v[90:93], v[152:155], v[202:205], v[90:93]
	v_mfma_f32_16x16x32_bf16 v[82:85], v[144:147], v[210:213], v[82:85]
	v_mfma_f32_16x16x32_bf16 v[74:77], v[152:155], v[210:213], v[74:77]
	v_mfma_f32_16x16x32_bf16 v[126:129], v[148:151], v[190:193], v[126:129]
	v_mfma_f32_16x16x32_bf16 v[122:125], v[156:159], v[190:193], v[122:125]
	v_mfma_f32_16x16x32_bf16 v[114:117], v[148:151], v[198:201], v[114:117]
	v_mfma_f32_16x16x32_bf16 v[106:109], v[156:159], v[198:201], v[106:109]
	v_mfma_f32_16x16x32_bf16 v[98:101], v[148:151], v[206:209], v[98:101]
	v_mfma_f32_16x16x32_bf16 v[90:93], v[156:159], v[206:209], v[90:93]
	v_mfma_f32_16x16x32_bf16 v[82:85], v[148:151], v[218:221], v[82:85]
	v_mfma_f32_16x16x32_bf16 v[74:77], v[156:159], v[218:221], v[74:77]
	s_setprio 0
	s_setprio 1
	v_mfma_f32_16x16x32_bf16 v[118:121], v[160:163], v[176:179], v[118:121]
	v_mfma_f32_16x16x32_bf16 v[110:113], v[168:171], v[176:179], v[110:113]
	v_mfma_f32_16x16x32_bf16 v[102:105], v[160:163], v[194:197], v[102:105]
	v_mfma_f32_16x16x32_bf16 v[94:97], v[168:171], v[194:197], v[94:97]
	v_mfma_f32_16x16x32_bf16 v[86:89], v[160:163], v[202:205], v[86:89]
	v_mfma_f32_16x16x32_bf16 v[78:81], v[168:171], v[202:205], v[78:81]
	v_mfma_f32_16x16x32_bf16 v[70:73], v[160:163], v[210:213], v[70:73]
	v_mfma_f32_16x16x32_bf16 v[66:69], v[168:171], v[210:213], v[66:69]
	v_mfma_f32_16x16x32_bf16 v[118:121], v[164:167], v[190:193], v[118:121]
	v_mfma_f32_16x16x32_bf16 v[110:113], v[172:175], v[190:193], v[110:113]
	v_mfma_f32_16x16x32_bf16 v[102:105], v[164:167], v[198:201], v[102:105]
	v_mfma_f32_16x16x32_bf16 v[94:97], v[172:175], v[198:201], v[94:97]
	v_mfma_f32_16x16x32_bf16 v[86:89], v[164:167], v[206:209], v[86:89]
	v_mfma_f32_16x16x32_bf16 v[78:81], v[172:175], v[206:209], v[78:81]
	v_mfma_f32_16x16x32_bf16 v[70:73], v[164:167], v[218:221], v[70:73]
	v_mfma_f32_16x16x32_bf16 v[66:69], v[172:175], v[218:221], v[66:69]
	s_barrier
	s_setprio 0
	s_add_i32 s18, s62, s5
	v_lshl_add_u64 v[214:215], s[8:9], 0, v[132:133]
	s_mov_b32 m0, s18
	ds_read_b128 v[176:179], v188 offset:16384
	ds_read_b128 v[190:193], v188 offset:17408
	ds_read_b128 v[194:197], v188 offset:18432
	ds_read_b128 v[198:201], v188 offset:19456
	ds_read_b128 v[202:205], v188 offset:20480
	ds_read_b128 v[206:209], v188 offset:21504
	ds_read_b128 v[210:213], v188 offset:22528
	ds_read_b128 v[218:221], v188 offset:23552
	global_load_lds_dwordx4 v[214:215], off
	s_add_i32 m0, s18, 0x2000
	s_add_u32 s18, s8, 0x100000
	v_lshl_add_u64 v[222:223], s[8:9], 0, v[136:137]
	s_addc_u32 s19, s9, 0
	s_add_i32 s20, s63, s5
	global_load_lds_dwordx4 v[222:223], off
	v_lshl_add_u64 v[224:225], s[18:19], 0, v[132:133]
	s_mov_b32 m0, s20
	v_lshl_add_u64 v[226:227], s[10:11], 0, v[134:135]
	global_load_lds_dwordx4 v[224:225], off
	v_lshl_add_u64 v[224:225], s[18:19], 0, v[136:137]
	s_add_i32 m0, s20, 0x2000
	s_nop 0
	global_load_lds_dwordx4 v[224:225], off
	v_lshl_add_u64 v[224:225], s[10:11], 0, v[130:131]
	s_mov_b32 m0, s41
	s_nop 0
	global_load_lds_dwordx4 v[224:225], off
	s_mov_b32 m0, s43
	s_nop 0
	global_load_lds_dwordx4 v[226:227], off
	s_waitcnt vmcnt(8)
	s_waitcnt lgkmcnt(0)
	s_setprio 1
	s_barrier
; #define PG8_STAGE(bufoff, gbase, voff) do { _Pragma("unroll") for (int _i = 0; _i < 2; ++_i) \
;         __builtin_amdgcn_global_load_lds((const unsigned*)((const char*)(gbase) + (voff)[_i]), (PG8_LAS unsigned*)(lds + (bufoff) + ldsw + _i * 8192), 16, 0, 0); } while (0)
; #define PG8_LDA(dst, b, h) do { _Pragma("unroll") for (int m = 0; m < 4; ++m) _Pragma("unroll") for (int k = 0; k < 2; ++k) dst[m][k] = *(const PG8_LAS bf16x8*)(lds + PG8_SA(b, h) + aoff + m * 2048 + k * 1024); } while (0)
; #define PG8_LDB(dst, b, h) do { _Pragma("unroll") for (int n = 0; n < 2; ++n) _Pragma("unroll") for (int k = 0; k < 2; ++k) dst[n][k] = *(const PG8_LAS bf16x8*)(lds + PG8_SB(b, h) + boff + n * 2048 + k * 1024); } while (0)
; #define PG8_MMA(ai, bj, At, Bt) do { __builtin_amdgcn_s_setprio(1); _Pragma("unroll") for (int m = 0; m < 4; ++m) _Pragma("unroll") for (int n = 0; n < 2; ++n) _Pragma("unroll") for (int k = 0; k < 2; ++k) \
;         acc[ai][bj][m][n] = __builtin_amdgcn_mfma_f32_16x16x32_bf16(Bt[n][k], At[m][k], acc[ai][bj][m][n], 0, 0, 0); __builtin_amdgcn_s_setprio(0); } while (0)
; #define PG8_WAIT_V(n) asm volatile("s_waitcnt vmcnt(" #n ")" ::: "memory")
; #define PG8_WAIT_L(n) asm volatile("s_waitcnt lgkmcnt(" #n ")" ::: "memory")
; #define PG8_BAR __builtin_amdgcn_s_barrier()
; #define PG8_SCHED __builtin_amdgcn_sched_barrier(0)
; template <class Epi, class Sched, bool ALIGN_EPI = false, bool SP2 = false>
; __device__ __forceinline__ void gemm_phase(PG8_LAS unsigned char* lds, const Gemm g, const Sched& S, const Epi& E) {
;     ...
;             PG8_WAIT_V(8); PG8_WAIT_L(0); PG8_BAR; PG8_MMA(1, 0, At, B0); PG8_MMA(1, 1, At, B1); PG8_BAR; PG8_SCHED;
;             PG8_LDB(B0, 1, 0); PG8_LDB(B1, 1, 1); PG8_SCHED; PG8_LDA(At, 1, 0); PG8_STAGE(PG8_SA(0, 1), a2 + hstep, voffA);
;             PG8_WAIT_V(8); PG8_WAIT_L(0); PG8_BAR; PG8_MMA(0, 0, At, B0); PG8_MMA(0, 1, At, B1); PG8_BAR; PG8_SCHED;
	v_mfma_f32_16x16x32_bf16 v[62:65], v[144:147], v[176:179], v[62:65]
	v_mfma_f32_16x16x32_bf16 v[58:61], v[152:155], v[176:179], v[58:61]
	v_mfma_f32_16x16x32_bf16 v[50:53], v[144:147], v[194:197], v[50:53]
	v_mfma_f32_16x16x32_bf16 v[42:45], v[152:155], v[194:197], v[42:45]
	v_mfma_f32_16x16x32_bf16 v[34:37], v[144:147], v[202:205], v[34:37]
	v_mfma_f32_16x16x32_bf16 v[26:29], v[152:155], v[202:205], v[26:29]
	v_mfma_f32_16x16x32_bf16 v[18:21], v[144:147], v[210:213], v[18:21]
	v_mfma_f32_16x16x32_bf16 v[10:13], v[152:155], v[210:213], v[10:13]
	v_mfma_f32_16x16x32_bf16 v[62:65], v[148:151], v[190:193], v[62:65]
	v_mfma_f32_16x16x32_bf16 v[58:61], v[156:159], v[190:193], v[58:61]
	v_mfma_f32_16x16x32_bf16 v[50:53], v[148:151], v[198:201], v[50:53]
	v_mfma_f32_16x16x32_bf16 v[42:45], v[156:159], v[198:201], v[42:45]
	v_mfma_f32_16x16x32_bf16 v[34:37], v[148:151], v[206:209], v[34:37]
	v_mfma_f32_16x16x32_bf16 v[26:29], v[156:159], v[206:209], v[26:29]
	v_mfma_f32_16x16x32_bf16 v[18:21], v[148:151], v[218:221], v[18:21]
	v_mfma_f32_16x16x32_bf16 v[10:13], v[156:159], v[218:221], v[10:13]
	s_setprio 0
	s_setprio 1
	v_mfma_f32_16x16x32_bf16 v[54:57], v[160:163], v[176:179], v[54:57]
	v_mfma_f32_16x16x32_bf16 v[46:49], v[168:171], v[176:179], v[46:49]
	v_mfma_f32_16x16x32_bf16 v[38:41], v[160:163], v[194:197], v[38:41]
	v_mfma_f32_16x16x32_bf16 v[30:33], v[168:171], v[194:197], v[30:33]
	v_mfma_f32_16x16x32_bf16 v[22:25], v[160:163], v[202:205], v[22:25]
	v_mfma_f32_16x16x32_bf16 v[14:17], v[168:171], v[202:205], v[14:17]
	v_mfma_f32_16x16x32_bf16 v[6:9], v[160:163], v[210:213], v[6:9]
	v_mfma_f32_16x16x32_bf16 v[2:5], v[168:171], v[210:213], v[2:5]
	v_mfma_f32_16x16x32_bf16 v[54:57], v[164:167], v[190:193], v[54:57]
	v_mfma_f32_16x16x32_bf16 v[46:49], v[172:175], v[190:193], v[46:49]
	v_mfma_f32_16x16x32_bf16 v[38:41], v[164:167], v[198:201], v[38:41]
	v_mfma_f32_16x16x32_bf16 v[30:33], v[172:175], v[198:201], v[30:33]
	v_mfma_f32_16x16x32_bf16 v[22:25], v[164:167], v[206:209], v[22:25]
	v_mfma_f32_16x16x32_bf16 v[14:17], v[172:175], v[206:209], v[14:17]
	v_mfma_f32_16x16x32_bf16 v[6:9], v[164:167], v[218:221], v[6:9]
	v_mfma_f32_16x16x32_bf16 v[2:5], v[172:175], v[218:221], v[2:5]
	s_barrier
	s_setprio 0
	s_add_i32 s18, 0, 0x18000
	v_add_u32_e32 v139, s18, v180
	s_add_i32 s19, 0, 0x1c000
	ds_read_b128 v[144:147], v139
	ds_read_b128 v[148:151], v139 offset:1024
	ds_read_b128 v[152:155], v139 offset:2048
	ds_read_b128 v[156:159], v139 offset:3072
	v_add_u32_e32 v139, s19, v180
	ds_read_b128 v[160:163], v139
	ds_read_b128 v[164:167], v139 offset:1024
	ds_read_b128 v[168:171], v139 offset:2048
	ds_read_b128 v[172:175], v139 offset:3072
	s_add_u32 s10, s10, 0x100000
	s_addc_u32 s11, s11, 0
	s_mov_b32 m0, s45
	v_lshl_add_u64 v[228:229], s[10:11], 0, v[130:131]
	ds_read_b128 v[176:179], v188 offset:32768
	ds_read_b128 v[190:193], v188 offset:33792
	ds_read_b128 v[194:197], v188 offset:34816
	ds_read_b128 v[198:201], v188 offset:35840
	ds_read_b128 v[202:205], v188 offset:36864
	ds_read_b128 v[206:209], v188 offset:37888
	ds_read_b128 v[210:213], v188 offset:38912
	ds_read_b128 v[218:221], v188 offset:39936
	global_load_lds_dwordx4 v[228:229], off
	v_lshl_add_u64 v[228:229], s[10:11], 0, v[134:135]
	s_mov_b32 m0, s47
	s_nop 0
	global_load_lds_dwordx4 v[228:229], off
	s_waitcnt vmcnt(8)
	s_waitcnt lgkmcnt(0)
	s_setprio 1
	s_barrier
	v_mfma_f32_16x16x32_bf16 v[126:129], v[144:147], v[176:179], v[126:129]
	v_mfma_f32_16x16x32_bf16 v[122:125], v[152:155], v[176:179], v[122:125]
	v_mfma_f32_16x16x32_bf16 v[114:117], v[144:147], v[194:197], v[114:117]
	v_mfma_f32_16x16x32_bf16 v[106:109], v[152:155], v[194:197], v[106:109]
	v_mfma_f32_16x16x32_bf16 v[98:101], v[144:147], v[202:205], v[98:101]
	v_mfma_f32_16x16x32_bf16 v[90:93], v[152:155], v[202:205], v[90:93]
	v_mfma_f32_16x16x32_bf16 v[82:85], v[144:147], v[210:213], v[82:85]
	v_mfma_f32_16x16x32_bf16 v[74:77], v[152:155], v[210:213], v[74:77]
	v_mfma_f32_16x16x32_bf16 v[126:129], v[148:151], v[190:193], v[126:129]
	v_mfma_f32_16x16x32_bf16 v[122:125], v[156:159], v[190:193], v[122:125]
	v_mfma_f32_16x16x32_bf16 v[114:117], v[148:151], v[198:201], v[114:117]
	v_mfma_f32_16x16x32_bf16 v[106:109], v[156:159], v[198:201], v[106:109]
	v_mfma_f32_16x16x32_bf16 v[98:101], v[148:151], v[206:209], v[98:101]
	v_mfma_f32_16x16x32_bf16 v[90:93], v[156:159], v[206:209], v[90:93]
	v_mfma_f32_16x16x32_bf16 v[82:85], v[148:151], v[218:221], v[82:85]
	v_mfma_f32_16x16x32_bf16 v[74:77], v[156:159], v[218:221], v[74:77]
	s_setprio 0
	s_setprio 1
	v_mfma_f32_16x16x32_bf16 v[118:121], v[160:163], v[176:179], v[118:121]
	v_mfma_f32_16x16x32_bf16 v[110:113], v[168:171], v[176:179], v[110:113]
	v_mfma_f32_16x16x32_bf16 v[102:105], v[160:163], v[194:197], v[102:105]
	v_mfma_f32_16x16x32_bf16 v[94:97], v[168:171], v[194:197], v[94:97]
	v_mfma_f32_16x16x32_bf16 v[86:89], v[160:163], v[202:205], v[86:89]
	v_mfma_f32_16x16x32_bf16 v[78:81], v[168:171], v[202:205], v[78:81]
	v_mfma_f32_16x16x32_bf16 v[70:73], v[160:163], v[210:213], v[70:73]
	v_mfma_f32_16x16x32_bf16 v[66:69], v[168:171], v[210:213], v[66:69]
	v_mfma_f32_16x16x32_bf16 v[118:121], v[164:167], v[190:193], v[118:121]
	v_mfma_f32_16x16x32_bf16 v[110:113], v[172:175], v[190:193], v[110:113]
	v_mfma_f32_16x16x32_bf16 v[102:105], v[164:167], v[198:201], v[102:105]
	v_mfma_f32_16x16x32_bf16 v[94:97], v[172:175], v[198:201], v[94:97]
	v_mfma_f32_16x16x32_bf16 v[86:89], v[164:167], v[206:209], v[86:89]
	v_mfma_f32_16x16x32_bf16 v[78:81], v[172:175], v[206:209], v[78:81]
	v_mfma_f32_16x16x32_bf16 v[70:73], v[164:167], v[218:221], v[70:73]
	v_mfma_f32_16x16x32_bf16 v[66:69], v[172:175], v[218:221], v[66:69]
	s_barrier
; #define PG8_STAGE(bufoff, gbase, voff) do { _Pragma("unroll") for (int _i = 0; _i < 2; ++_i) \
;         __builtin_amdgcn_global_load_lds((const unsigned*)((const char*)(gbase) + (voff)[_i]), (PG8_LAS unsigned*)(lds + (bufoff) + ldsw + _i * 8192), 16, 0, 0); } while (0)
; #define PG8_LDA(dst, b, h) do { _Pragma("unroll") for (int m = 0; m < 4; ++m) _Pragma("unroll") for (int k = 0; k < 2; ++k) dst[m][k] = *(const PG8_LAS bf16x8*)(lds + PG8_SA(b, h) + aoff + m * 2048 + k * 1024); } while (0)
; #define PG8_MMA(ai, bj, At, Bt) do { __builtin_amdgcn_s_setprio(1); _Pragma("unroll") for (int m = 0; m < 4; ++m) _Pragma("unroll") for (int n = 0; n < 2; ++n) _Pragma("unroll") for (int k = 0; k < 2; ++k) \
;         acc[ai][bj][m][n] = __builtin_amdgcn_mfma_f32_16x16x32_bf16(Bt[n][k], At[m][k], acc[ai][bj][m][n], 0, 0, 0); __builtin_amdgcn_s_setprio(0); } while (0)
; #define PG8_WAIT_V(n) asm volatile("s_waitcnt vmcnt(" #n ")" ::: "memory")
; #define PG8_WAIT_L(n) asm volatile("s_waitcnt lgkmcnt(" #n ")" ::: "memory")
; #define PG8_BAR __builtin_amdgcn_s_barrier()
; #define PG8_SCHED __builtin_amdgcn_sched_barrier(0)
; template <class Epi, class Sched, bool ALIGN_EPI = false, bool SP2 = false>
; __device__ __forceinline__ void gemm_phase(PG8_LAS unsigned char* lds, const Gemm g, const Sched& S, const Epi& E) {
;     ...
;             PG8_LDA(At, 1, 1); PG8_STAGE(PG8_SB(1, 0), b3, voffB); PG8_STAGE(PG8_SB(1, 1), b3 + hstep, voffB); PG8_STAGE(PG8_SA(1, 0), a3, voffA);
;             PG8_WAIT_V(8); PG8_WAIT_L(0); PG8_BAR; PG8_MMA(1, 0, At, B0); PG8_MMA(1, 1, At, B1); PG8_BAR; PG8_SCHED;
;     ...
;         if constexpr (ALIGN_EPI) { if (wr == 0) PG8_BAR; }
;         if constexpr (!Epi::AFTER_DRAIN) { E(acc, cur, wr, wc, fr, fq); S.done(cur); }
;         if (!has_next) break;
	s_setprio 0
	s_add_i32 s10, s18, s5
	v_lshl_add_u64 v[214:215], v[214:215], 0, s[50:51]
	s_mov_b32 m0, s10
	ds_read_b128 v[176:179], v188 offset:49152
	ds_read_b128 v[190:193], v188 offset:50176
	ds_read_b128 v[194:197], v188 offset:51200
	ds_read_b128 v[198:201], v188 offset:52224
	ds_read_b128 v[202:205], v188 offset:53248
	ds_read_b128 v[206:209], v188 offset:54272
	ds_read_b128 v[210:213], v188 offset:55296
	ds_read_b128 v[218:221], v188 offset:56320
	global_load_lds_dwordx4 v[214:215], off
	s_add_i32 m0, s10, 0x2000
	s_add_u32 s8, s8, 0x100080
	v_lshl_add_u64 v[214:215], v[222:223], 0, s[50:51]
	s_addc_u32 s9, s9, 0
	s_add_i32 s10, s19, s5
	global_load_lds_dwordx4 v[214:215], off
	v_lshl_add_u64 v[214:215], s[8:9], 0, v[132:133]
	s_mov_b32 m0, s10
	s_nop 0
	global_load_lds_dwordx4 v[214:215], off
	v_lshl_add_u64 v[214:215], s[8:9], 0, v[136:137]
	s_add_i32 m0, s10, 0x2000
	s_nop 0
	global_load_lds_dwordx4 v[214:215], off
	v_lshl_add_u64 v[214:215], v[224:225], 0, s[50:51]
	s_mov_b32 m0, s55
	s_nop 0
	global_load_lds_dwordx4 v[214:215], off
	v_lshl_add_u64 v[214:215], v[226:227], 0, s[50:51]
	s_mov_b32 m0, s57
	s_nop 0
	global_load_lds_dwordx4 v[214:215], off
	s_waitcnt vmcnt(8)
	s_waitcnt lgkmcnt(0)
	s_setprio 1
	s_barrier
	v_mfma_f32_16x16x32_bf16 v[62:65], v[144:147], v[176:179], v[62:65]
	v_mfma_f32_16x16x32_bf16 v[58:61], v[152:155], v[176:179], v[58:61]
	v_mfma_f32_16x16x32_bf16 v[50:53], v[144:147], v[194:197], v[50:53]
	v_mfma_f32_16x16x32_bf16 v[42:45], v[152:155], v[194:197], v[42:45]
	v_mfma_f32_16x16x32_bf16 v[34:37], v[144:147], v[202:205], v[34:37]
	v_mfma_f32_16x16x32_bf16 v[26:29], v[152:155], v[202:205], v[26:29]
	v_mfma_f32_16x16x32_bf16 v[18:21], v[144:147], v[210:213], v[18:21]
	v_mfma_f32_16x16x32_bf16 v[10:13], v[152:155], v[210:213], v[10:13]
	v_mfma_f32_16x16x32_bf16 v[62:65], v[148:151], v[190:193], v[62:65]
	v_mfma_f32_16x16x32_bf16 v[58:61], v[156:159], v[190:193], v[58:61]
	v_mfma_f32_16x16x32_bf16 v[50:53], v[148:151], v[198:201], v[50:53]
	v_mfma_f32_16x16x32_bf16 v[42:45], v[156:159], v[198:201], v[42:45]
	v_mfma_f32_16x16x32_bf16 v[34:37], v[148:151], v[206:209], v[34:37]
	v_mfma_f32_16x16x32_bf16 v[26:29], v[156:159], v[206:209], v[26:29]
	v_mfma_f32_16x16x32_bf16 v[18:21], v[148:151], v[218:221], v[18:21]
	v_mfma_f32_16x16x32_bf16 v[10:13], v[156:159], v[218:221], v[10:13]
	s_setprio 0
	s_setprio 1
	v_mfma_f32_16x16x32_bf16 v[54:57], v[160:163], v[176:179], v[54:57]
	v_mfma_f32_16x16x32_bf16 v[46:49], v[168:171], v[176:179], v[46:49]
	v_mfma_f32_16x16x32_bf16 v[38:41], v[160:163], v[194:197], v[38:41]
	v_mfma_f32_16x16x32_bf16 v[30:33], v[168:171], v[194:197], v[30:33]
	v_mfma_f32_16x16x32_bf16 v[22:25], v[160:163], v[202:205], v[22:25]
	v_mfma_f32_16x16x32_bf16 v[14:17], v[168:171], v[202:205], v[14:17]
	v_mfma_f32_16x16x32_bf16 v[6:9], v[160:163], v[210:213], v[6:9]
	v_mfma_f32_16x16x32_bf16 v[2:5], v[168:171], v[210:213], v[2:5]
	v_mfma_f32_16x16x32_bf16 v[54:57], v[164:167], v[190:193], v[54:57]
	v_mfma_f32_16x16x32_bf16 v[46:49], v[172:175], v[190:193], v[46:49]
	v_mfma_f32_16x16x32_bf16 v[38:41], v[164:167], v[198:201], v[38:41]
	v_mfma_f32_16x16x32_bf16 v[30:33], v[172:175], v[198:201], v[30:33]
	v_mfma_f32_16x16x32_bf16 v[22:25], v[164:167], v[206:209], v[22:25]
	v_mfma_f32_16x16x32_bf16 v[14:17], v[172:175], v[206:209], v[14:17]
	v_mfma_f32_16x16x32_bf16 v[6:9], v[164:167], v[218:221], v[6:9]
	v_mfma_f32_16x16x32_bf16 v[2:5], v[172:175], v[218:221], v[2:5]
	s_barrier
	s_setprio 0
	s_add_i32 s17, s17, 2
	s_add_u32 s6, s6, 0x100
	s_addc_u32 s7, s7, 0
	s_add_u32 s15, s15, 0x100
	s_addc_u32 s16, s16, 0
	s_cmp_gt_u32 s17, 61
	s_cbranch_scc0 .LBB0_183
	s_and_b64 vcc, exec, s[22:23]
	s_cbranch_vccnz .LBB0_188
	v_lshl_add_u32 v144, s0, 8, v1
	s_cmp_gt_i32 s40, 3
	s_mov_b64 s[0:1], -1
	s_cbranch_scc1 .LBB0_189

; #define PG8_STAGE(bufoff, gbase, voff) do { _Pragma("unroll") for (int _i = 0; _i < 2; ++_i) \
;         __builtin_amdgcn_global_load_lds((const unsigned*)((const char*)(gbase) + (voff)[_i]), (PG8_LAS unsigned*)(lds + (bufoff) + ldsw + _i * 8192), 16, 0, 0); } while (0)
; #define PG8_LDA(dst, b, h) do { _Pragma("unroll") for (int m = 0; m < 4; ++m) _Pragma("unroll") for (int k = 0; k < 2; ++k) dst[m][k] = *(const PG8_LAS bf16x8*)(lds + PG8_SA(b, h) + aoff + m * 2048 + k * 1024); } while (0)
; #define PG8_LDB(dst, b, h) do { _Pragma("unroll") for (int n = 0; n < 2; ++n) _Pragma("unroll") for (int k = 0; k < 2; ++k) dst[n][k] = *(const PG8_LAS bf16x8*)(lds + PG8_SB(b, h) + boff + n * 2048 + k * 1024); } while (0)
; #define PG8_MMA(ai, bj, At, Bt) do { __builtin_amdgcn_s_setprio(1); _Pragma("unroll") for (int m = 0; m < 4; ++m) _Pragma("unroll") for (int n = 0; n < 2; ++n) _Pragma("unroll") for (int k = 0; k < 2; ++k) \
;         acc[ai][bj][m][n] = __builtin_amdgcn_mfma_f32_16x16x32_bf16(Bt[n][k], At[m][k], acc[ai][bj][m][n], 0, 0, 0); __builtin_amdgcn_s_setprio(0); } while (0)
; #define PG8_WAIT_V(n) asm volatile("s_waitcnt vmcnt(" #n ")" ::: "memory")
; #define PG8_WAIT_L(n) asm volatile("s_waitcnt lgkmcnt(" #n ")" ::: "memory")
; template <class Epi, class Sched, bool ALIGN_EPI = false, bool SP2 = false>
; __device__ __forceinline__ void gemm_phase(PG8_LAS unsigned char* lds, const Gemm g, const Sched& S, const Epi& E) {
;     ...
;             const bool last = (t == nt - 2);
;             const char* a1 = cA + (size_t)(t + 1) * kstep;
;             const char* a2 = last ? nA : cA + (size_t)(t + 2) * kstep; const char* b2 = last ? nB : cB + (size_t)(t + 2) * kstep;
;             const char* a3 = a2 + kstep; const char* b3 = b2 + kstep;
;             if (last && has_next) S.a_ready(nxt);
;             if constexpr (SP2) {
;             PG8_LDB(B0, 0, 0); PG8_LDB(B1, 0, 1); PG8_SCHED; PG8_LDA(At, 0, 0); PG8_STAGE(PG8_SA(1, 1), a1 + hstep, voffA);
;             PG8_WAIT_V(8); PG8_WAIT_L(0); PG8_BAR; PG8_MMA(0, 0, At, B0); PG8_MMA(0, 1, At, B1); PG8_BAR; PG8_SCHED;
;             PG8_LDA(At, 0, 1); PG8_STAGE(PG8_SB(0, 0), b2, voffB); PG8_STAGE(PG8_SB(0, 1), b2 + hstep, voffB); PG8_STAGE(PG8_SA(0, 0), a2, voffA);
;             PG8_WAIT_V(8); PG8_WAIT_L(0); PG8_BAR; PG8_MMA(1, 0, At, B0); PG8_MMA(1, 1, At, B1); PG8_BAR; PG8_SCHED;
.LBB0_292:
	ds_read_b128 v[146:149], v164
	ds_read_b128 v[150:153], v164 offset:1024
	s_waitcnt lgkmcnt(0)
	ds_read_b128 v[154:157], v164 offset:2048
	ds_read_b128 v[168:171], v164 offset:3072
	ds_read_b128 v[172:175], v165
	ds_read_b128 v[176:179], v165 offset:1024
	ds_read_b128 v[180:183], v165 offset:2048
	ds_read_b128 v[184:187], v165 offset:3072
	s_add_u32 s40, s38, 0xfff00080
	s_addc_u32 s41, s39, -1
	s_cmp_eq_u32 s71, 60
	s_cselect_b32 s43, s33, s41
	s_cselect_b32 s42, s53, s40
	s_cselect_b32 s41, s51, s69
	s_cselect_b32 s40, s61, s68
	v_lshl_add_u64 v[222:223], s[38:39], 0, v[142:143]
	s_add_i32 m0, s19, 0xc000
	ds_read_b128 v[188:191], v166
	ds_read_b128 v[192:195], v166 offset:1024
	ds_read_b128 v[196:199], v166 offset:2048
	ds_read_b128 v[200:203], v166 offset:3072
	ds_read_b128 v[204:207], v166 offset:4096
	ds_read_b128 v[208:211], v166 offset:5120
	ds_read_b128 v[212:215], v166 offset:6144
	ds_read_b128 v[218:221], v166 offset:7168
	global_load_lds_dwordx4 v[222:223], off
	v_lshl_add_u64 v[222:223], s[38:39], 0, v[144:145]
	s_add_i32 m0, s19, 0xe000
	s_nop 0
	global_load_lds_dwordx4 v[222:223], off
	s_waitcnt vmcnt(8)
	s_waitcnt lgkmcnt(0)
	s_setprio 1
	s_barrier
	v_mfma_f32_16x16x32_bf16 v[126:129], v[146:149], v[188:191], v[126:129]
	v_mfma_f32_16x16x32_bf16 v[122:125], v[154:157], v[188:191], v[122:125]
	v_mfma_f32_16x16x32_bf16 v[118:121], v[146:149], v[196:199], v[118:121]
	v_mfma_f32_16x16x32_bf16 v[110:113], v[154:157], v[196:199], v[110:113]
	v_mfma_f32_16x16x32_bf16 v[102:105], v[146:149], v[204:207], v[102:105]
	v_mfma_f32_16x16x32_bf16 v[94:97], v[154:157], v[204:207], v[94:97]
	v_mfma_f32_16x16x32_bf16 v[86:89], v[146:149], v[212:215], v[86:89]
	v_mfma_f32_16x16x32_bf16 v[78:81], v[154:157], v[212:215], v[78:81]
	v_mfma_f32_16x16x32_bf16 v[126:129], v[150:153], v[192:195], v[126:129]
	v_mfma_f32_16x16x32_bf16 v[122:125], v[168:171], v[192:195], v[122:125]
	v_mfma_f32_16x16x32_bf16 v[118:121], v[150:153], v[200:203], v[118:121]
	v_mfma_f32_16x16x32_bf16 v[110:113], v[168:171], v[200:203], v[110:113]
	v_mfma_f32_16x16x32_bf16 v[102:105], v[150:153], v[208:211], v[102:105]
	v_mfma_f32_16x16x32_bf16 v[94:97], v[168:171], v[208:211], v[94:97]
	v_mfma_f32_16x16x32_bf16 v[86:89], v[150:153], v[218:221], v[86:89]
	v_mfma_f32_16x16x32_bf16 v[78:81], v[168:171], v[218:221], v[78:81]
	s_setprio 0
	s_setprio 1
	v_mfma_f32_16x16x32_bf16 v[114:117], v[172:175], v[188:191], v[114:117]
	v_mfma_f32_16x16x32_bf16 v[106:109], v[180:183], v[188:191], v[106:109]
	v_mfma_f32_16x16x32_bf16 v[98:101], v[172:175], v[196:199], v[98:101]
	v_mfma_f32_16x16x32_bf16 v[90:93], v[180:183], v[196:199], v[90:93]
	v_mfma_f32_16x16x32_bf16 v[82:85], v[172:175], v[204:207], v[82:85]
	v_mfma_f32_16x16x32_bf16 v[74:77], v[180:183], v[204:207], v[74:77]
	v_mfma_f32_16x16x32_bf16 v[70:73], v[172:175], v[212:215], v[70:73]
	v_mfma_f32_16x16x32_bf16 v[66:69], v[180:183], v[212:215], v[66:69]
	v_mfma_f32_16x16x32_bf16 v[114:117], v[176:179], v[192:195], v[114:117]
	v_mfma_f32_16x16x32_bf16 v[106:109], v[184:187], v[192:195], v[106:109]
	v_mfma_f32_16x16x32_bf16 v[98:101], v[176:179], v[200:203], v[98:101]
	v_mfma_f32_16x16x32_bf16 v[90:93], v[184:187], v[200:203], v[90:93]
	v_mfma_f32_16x16x32_bf16 v[82:85], v[176:179], v[208:211], v[82:85]
	v_mfma_f32_16x16x32_bf16 v[74:77], v[184:187], v[208:211], v[74:77]
	v_mfma_f32_16x16x32_bf16 v[70:73], v[176:179], v[218:221], v[70:73]
	v_mfma_f32_16x16x32_bf16 v[66:69], v[184:187], v[218:221], v[66:69]
	s_barrier
	s_setprio 0
	s_add_i32 s72, s45, s17
	v_lshl_add_u64 v[222:223], s[40:41], 0, v[132:133]
	s_mov_b32 m0, s72
	ds_read_b128 v[188:191], v166 offset:16384
	ds_read_b128 v[192:195], v166 offset:17408
	ds_read_b128 v[196:199], v166 offset:18432
	ds_read_b128 v[200:203], v166 offset:19456
	ds_read_b128 v[204:207], v166 offset:20480
	ds_read_b128 v[208:211], v166 offset:21504
	ds_read_b128 v[212:215], v166 offset:22528
	ds_read_b128 v[218:221], v166 offset:23552
	global_load_lds_dwordx4 v[222:223], off
	s_add_i32 m0, s72, 0x2000
	s_add_u32 s72, s40, 0x100000
	v_lshl_add_u64 v[224:225], s[40:41], 0, v[136:137]
	s_addc_u32 s73, s41, 0
	s_add_i32 s74, s55, s17
	global_load_lds_dwordx4 v[224:225], off
	v_lshl_add_u64 v[226:227], s[72:73], 0, v[132:133]
	s_mov_b32 m0, s74
	v_lshl_add_u64 v[228:229], s[42:43], 0, v[134:135]
	global_load_lds_dwordx4 v[226:227], off
	v_lshl_add_u64 v[226:227], s[72:73], 0, v[136:137]
	s_add_i32 m0, s74, 0x2000
	s_nop 0
	global_load_lds_dwordx4 v[226:227], off
	v_lshl_add_u64 v[226:227], s[42:43], 0, v[130:131]
	s_mov_b32 m0, s19
	s_nop 0
	global_load_lds_dwordx4 v[226:227], off
	s_mov_b32 m0, s21
	s_nop 0
	global_load_lds_dwordx4 v[228:229], off
	s_waitcnt vmcnt(8)
	s_waitcnt lgkmcnt(0)
	s_setprio 1
	s_barrier
; #define PG8_STAGE(bufoff, gbase, voff) do { _Pragma("unroll") for (int _i = 0; _i < 2; ++_i) \
;         __builtin_amdgcn_global_load_lds((const unsigned*)((const char*)(gbase) + (voff)[_i]), (PG8_LAS unsigned*)(lds + (bufoff) + ldsw + _i * 8192), 16, 0, 0); } while (0)
; #define PG8_LDA(dst, b, h) do { _Pragma("unroll") for (int m = 0; m < 4; ++m) _Pragma("unroll") for (int k = 0; k < 2; ++k) dst[m][k] = *(const PG8_LAS bf16x8*)(lds + PG8_SA(b, h) + aoff + m * 2048 + k * 1024); } while (0)
; #define PG8_LDB(dst, b, h) do { _Pragma("unroll") for (int n = 0; n < 2; ++n) _Pragma("unroll") for (int k = 0; k < 2; ++k) dst[n][k] = *(const PG8_LAS bf16x8*)(lds + PG8_SB(b, h) + boff + n * 2048 + k * 1024); } while (0)
; #define PG8_MMA(ai, bj, At, Bt) do { __builtin_amdgcn_s_setprio(1); _Pragma("unroll") for (int m = 0; m < 4; ++m) _Pragma("unroll") for (int n = 0; n < 2; ++n) _Pragma("unroll") for (int k = 0; k < 2; ++k) \
;         acc[ai][bj][m][n] = __builtin_amdgcn_mfma_f32_16x16x32_bf16(Bt[n][k], At[m][k], acc[ai][bj][m][n], 0, 0, 0); __builtin_amdgcn_s_setprio(0); } while (0)
; #define PG8_WAIT_V(n) asm volatile("s_waitcnt vmcnt(" #n ")" ::: "memory")
; #define PG8_WAIT_L(n) asm volatile("s_waitcnt lgkmcnt(" #n ")" ::: "memory")
; #define PG8_BAR __builtin_amdgcn_s_barrier()
; #define PG8_SCHED __builtin_amdgcn_sched_barrier(0)
; template <class Epi, class Sched, bool ALIGN_EPI = false, bool SP2 = false>
; __device__ __forceinline__ void gemm_phase(PG8_LAS unsigned char* lds, const Gemm g, const Sched& S, const Epi& E) {
;     ...
;             PG8_WAIT_V(8); PG8_WAIT_L(0); PG8_BAR; PG8_MMA(1, 0, At, B0); PG8_MMA(1, 1, At, B1); PG8_BAR; PG8_SCHED;
;             PG8_LDB(B0, 1, 0); PG8_LDB(B1, 1, 1); PG8_SCHED; PG8_LDA(At, 1, 0); PG8_STAGE(PG8_SA(0, 1), a2 + hstep, voffA);
;             PG8_WAIT_V(8); PG8_WAIT_L(0); PG8_BAR; PG8_MMA(0, 0, At, B0); PG8_MMA(0, 1, At, B1); PG8_BAR; PG8_SCHED;
	v_mfma_f32_16x16x32_bf16 v[62:65], v[146:149], v[188:191], v[62:65]
	v_mfma_f32_16x16x32_bf16 v[58:61], v[154:157], v[188:191], v[58:61]
	v_mfma_f32_16x16x32_bf16 v[54:57], v[146:149], v[196:199], v[54:57]
	v_mfma_f32_16x16x32_bf16 v[46:49], v[154:157], v[196:199], v[46:49]
	v_mfma_f32_16x16x32_bf16 v[38:41], v[146:149], v[204:207], v[38:41]
	v_mfma_f32_16x16x32_bf16 v[30:33], v[154:157], v[204:207], v[30:33]
	v_mfma_f32_16x16x32_bf16 v[22:25], v[146:149], v[212:215], v[22:25]
	v_mfma_f32_16x16x32_bf16 v[14:17], v[154:157], v[212:215], v[14:17]
	v_mfma_f32_16x16x32_bf16 v[62:65], v[150:153], v[192:195], v[62:65]
	v_mfma_f32_16x16x32_bf16 v[58:61], v[168:171], v[192:195], v[58:61]
	v_mfma_f32_16x16x32_bf16 v[54:57], v[150:153], v[200:203], v[54:57]
	v_mfma_f32_16x16x32_bf16 v[46:49], v[168:171], v[200:203], v[46:49]
	v_mfma_f32_16x16x32_bf16 v[38:41], v[150:153], v[208:211], v[38:41]
	v_mfma_f32_16x16x32_bf16 v[30:33], v[168:171], v[208:211], v[30:33]
	v_mfma_f32_16x16x32_bf16 v[22:25], v[150:153], v[218:221], v[22:25]
	v_mfma_f32_16x16x32_bf16 v[14:17], v[168:171], v[218:221], v[14:17]
	s_setprio 0
	s_setprio 1
	v_mfma_f32_16x16x32_bf16 v[50:53], v[172:175], v[188:191], v[50:53]
	v_mfma_f32_16x16x32_bf16 v[42:45], v[180:183], v[188:191], v[42:45]
	v_mfma_f32_16x16x32_bf16 v[34:37], v[172:175], v[196:199], v[34:37]
	v_mfma_f32_16x16x32_bf16 v[26:29], v[180:183], v[196:199], v[26:29]
	v_mfma_f32_16x16x32_bf16 v[18:21], v[172:175], v[204:207], v[18:21]
	v_mfma_f32_16x16x32_bf16 v[10:13], v[180:183], v[204:207], v[10:13]
	v_mfma_f32_16x16x32_bf16 v[6:9], v[172:175], v[212:215], v[6:9]
	v_mfma_f32_16x16x32_bf16 v[2:5], v[180:183], v[212:215], v[2:5]
	v_mfma_f32_16x16x32_bf16 v[50:53], v[176:179], v[192:195], v[50:53]
	v_mfma_f32_16x16x32_bf16 v[42:45], v[184:187], v[192:195], v[42:45]
	v_mfma_f32_16x16x32_bf16 v[34:37], v[176:179], v[200:203], v[34:37]
	v_mfma_f32_16x16x32_bf16 v[26:29], v[184:187], v[200:203], v[26:29]
	v_mfma_f32_16x16x32_bf16 v[18:21], v[176:179], v[208:211], v[18:21]
	v_mfma_f32_16x16x32_bf16 v[10:13], v[184:187], v[208:211], v[10:13]
	v_mfma_f32_16x16x32_bf16 v[6:9], v[176:179], v[218:221], v[6:9]
	v_mfma_f32_16x16x32_bf16 v[2:5], v[184:187], v[218:221], v[2:5]
	s_barrier
	s_setprio 0
	s_add_i32 s72, 0, 0x18000
	v_add_u32_e32 v139, s72, v158
	s_add_i32 s73, 0, 0x1c000
	ds_read_b128 v[146:149], v139
	ds_read_b128 v[150:153], v139 offset:1024
	ds_read_b128 v[154:157], v139 offset:2048
	ds_read_b128 v[168:171], v139 offset:3072
	v_add_u32_e32 v139, s73, v158
	ds_read_b128 v[172:175], v139
	ds_read_b128 v[176:179], v139 offset:1024
	ds_read_b128 v[180:183], v139 offset:2048
	ds_read_b128 v[184:187], v139 offset:3072
	s_add_u32 s42, s42, 0x100000
	s_addc_u32 s43, s43, 0
	s_mov_b32 m0, s23
	v_lshl_add_u64 v[230:231], s[42:43], 0, v[130:131]
	ds_read_b128 v[188:191], v166 offset:32768
	ds_read_b128 v[192:195], v166 offset:33792
	ds_read_b128 v[196:199], v166 offset:34816
	ds_read_b128 v[200:203], v166 offset:35840
	ds_read_b128 v[204:207], v166 offset:36864
	ds_read_b128 v[208:211], v166 offset:37888
	ds_read_b128 v[212:215], v166 offset:38912
	ds_read_b128 v[218:221], v166 offset:39936
	global_load_lds_dwordx4 v[230:231], off
	v_lshl_add_u64 v[230:231], s[42:43], 0, v[134:135]
	s_mov_b32 m0, s25
	s_nop 0
	global_load_lds_dwordx4 v[230:231], off
	s_waitcnt vmcnt(8)
	s_waitcnt lgkmcnt(0)
	s_setprio 1
	s_barrier
	v_mfma_f32_16x16x32_bf16 v[126:129], v[146:149], v[188:191], v[126:129]
	v_mfma_f32_16x16x32_bf16 v[122:125], v[154:157], v[188:191], v[122:125]
	v_mfma_f32_16x16x32_bf16 v[118:121], v[146:149], v[196:199], v[118:121]
	v_mfma_f32_16x16x32_bf16 v[110:113], v[154:157], v[196:199], v[110:113]
	v_mfma_f32_16x16x32_bf16 v[102:105], v[146:149], v[204:207], v[102:105]
	v_mfma_f32_16x16x32_bf16 v[94:97], v[154:157], v[204:207], v[94:97]
	v_mfma_f32_16x16x32_bf16 v[86:89], v[146:149], v[212:215], v[86:89]
	v_mfma_f32_16x16x32_bf16 v[78:81], v[154:157], v[212:215], v[78:81]
	v_mfma_f32_16x16x32_bf16 v[126:129], v[150:153], v[192:195], v[126:129]
	v_mfma_f32_16x16x32_bf16 v[122:125], v[168:171], v[192:195], v[122:125]
	v_mfma_f32_16x16x32_bf16 v[118:121], v[150:153], v[200:203], v[118:121]
	v_mfma_f32_16x16x32_bf16 v[110:113], v[168:171], v[200:203], v[110:113]
	v_mfma_f32_16x16x32_bf16 v[102:105], v[150:153], v[208:211], v[102:105]
	v_mfma_f32_16x16x32_bf16 v[94:97], v[168:171], v[208:211], v[94:97]
	v_mfma_f32_16x16x32_bf16 v[86:89], v[150:153], v[218:221], v[86:89]
	v_mfma_f32_16x16x32_bf16 v[78:81], v[168:171], v[218:221], v[78:81]
	s_setprio 0
	s_setprio 1
	v_mfma_f32_16x16x32_bf16 v[114:117], v[172:175], v[188:191], v[114:117]
	v_mfma_f32_16x16x32_bf16 v[106:109], v[180:183], v[188:191], v[106:109]
	v_mfma_f32_16x16x32_bf16 v[98:101], v[172:175], v[196:199], v[98:101]
	v_mfma_f32_16x16x32_bf16 v[90:93], v[180:183], v[196:199], v[90:93]
	v_mfma_f32_16x16x32_bf16 v[82:85], v[172:175], v[204:207], v[82:85]
	v_mfma_f32_16x16x32_bf16 v[74:77], v[180:183], v[204:207], v[74:77]
	v_mfma_f32_16x16x32_bf16 v[70:73], v[172:175], v[212:215], v[70:73]
	v_mfma_f32_16x16x32_bf16 v[66:69], v[180:183], v[212:215], v[66:69]
	v_mfma_f32_16x16x32_bf16 v[114:117], v[176:179], v[192:195], v[114:117]
	v_mfma_f32_16x16x32_bf16 v[106:109], v[184:187], v[192:195], v[106:109]
	v_mfma_f32_16x16x32_bf16 v[98:101], v[176:179], v[200:203], v[98:101]
	v_mfma_f32_16x16x32_bf16 v[90:93], v[184:187], v[200:203], v[90:93]
	v_mfma_f32_16x16x32_bf16 v[82:85], v[176:179], v[208:211], v[82:85]
	v_mfma_f32_16x16x32_bf16 v[74:77], v[184:187], v[208:211], v[74:77]
	v_mfma_f32_16x16x32_bf16 v[70:73], v[176:179], v[218:221], v[70:73]
	v_mfma_f32_16x16x32_bf16 v[66:69], v[184:187], v[218:221], v[66:69]
	s_barrier
; #define PG8_STAGE(bufoff, gbase, voff) do { _Pragma("unroll") for (int _i = 0; _i < 2; ++_i) \
;         __builtin_amdgcn_global_load_lds((const unsigned*)((const char*)(gbase) + (voff)[_i]), (PG8_LAS unsigned*)(lds + (bufoff) + ldsw + _i * 8192), 16, 0, 0); } while (0)
; #define PG8_LDA(dst, b, h) do { _Pragma("unroll") for (int m = 0; m < 4; ++m) _Pragma("unroll") for (int k = 0; k < 2; ++k) dst[m][k] = *(const PG8_LAS bf16x8*)(lds + PG8_SA(b, h) + aoff + m * 2048 + k * 1024); } while (0)
; #define PG8_MMA(ai, bj, At, Bt) do { __builtin_amdgcn_s_setprio(1); _Pragma("unroll") for (int m = 0; m < 4; ++m) _Pragma("unroll") for (int n = 0; n < 2; ++n) _Pragma("unroll") for (int k = 0; k < 2; ++k) \
;         acc[ai][bj][m][n] = __builtin_amdgcn_mfma_f32_16x16x32_bf16(Bt[n][k], At[m][k], acc[ai][bj][m][n], 0, 0, 0); __builtin_amdgcn_s_setprio(0); } while (0)
; #define PG8_WAIT_V(n) asm volatile("s_waitcnt vmcnt(" #n ")" ::: "memory")
; #define PG8_WAIT_L(n) asm volatile("s_waitcnt lgkmcnt(" #n ")" ::: "memory")
; #define PG8_BAR __builtin_amdgcn_s_barrier()
; #define PG8_SCHED __builtin_amdgcn_sched_barrier(0)
; template <class Epi, class Sched, bool ALIGN_EPI = false, bool SP2 = false>
; __device__ __forceinline__ void gemm_phase(PG8_LAS unsigned char* lds, const Gemm g, const Sched& S, const Epi& E) {
;     ...
;             PG8_LDA(At, 1, 1); PG8_STAGE(PG8_SB(1, 0), b3, voffB); PG8_STAGE(PG8_SB(1, 1), b3 + hstep, voffB); PG8_STAGE(PG8_SA(1, 0), a3, voffA);
;             PG8_WAIT_V(8); PG8_WAIT_L(0); PG8_BAR; PG8_MMA(1, 0, At, B0); PG8_MMA(1, 1, At, B1); PG8_BAR; PG8_SCHED;
;     ...
;         if constexpr (ALIGN_EPI) { if (wr == 0) PG8_BAR; }
;         if constexpr (!Epi::AFTER_DRAIN) { E(acc, cur, wr, wc, fr, fq); S.done(cur); }
;         if (!has_next) break;
	s_setprio 0
	s_add_i32 s42, s72, s17
	v_lshl_add_u64 v[222:223], v[222:223], 0, s[10:11]
	s_mov_b32 m0, s42
	ds_read_b128 v[188:191], v166 offset:49152
	ds_read_b128 v[192:195], v166 offset:50176
	ds_read_b128 v[196:199], v166 offset:51200
	ds_read_b128 v[200:203], v166 offset:52224
	ds_read_b128 v[204:207], v166 offset:53248
	ds_read_b128 v[208:211], v166 offset:54272
	ds_read_b128 v[212:215], v166 offset:55296
	ds_read_b128 v[218:221], v166 offset:56320
	global_load_lds_dwordx4 v[222:223], off
	s_add_i32 m0, s42, 0x2000
	s_add_u32 s40, s40, 0x100080
	v_lshl_add_u64 v[222:223], v[224:225], 0, s[10:11]
	s_addc_u32 s41, s41, 0
	s_add_i32 s42, s73, s17
	global_load_lds_dwordx4 v[222:223], off
	v_lshl_add_u64 v[222:223], s[40:41], 0, v[132:133]
	s_mov_b32 m0, s42
	s_nop 0
	global_load_lds_dwordx4 v[222:223], off
	v_lshl_add_u64 v[222:223], s[40:41], 0, v[136:137]
	s_add_i32 m0, s42, 0x2000
	s_nop 0
	global_load_lds_dwordx4 v[222:223], off
	v_lshl_add_u64 v[222:223], v[226:227], 0, s[10:11]
	s_mov_b32 m0, s27
	s_nop 0
	global_load_lds_dwordx4 v[222:223], off
	v_lshl_add_u64 v[222:223], v[228:229], 0, s[10:11]
	s_mov_b32 m0, s29
	s_nop 0
	global_load_lds_dwordx4 v[222:223], off
	s_waitcnt vmcnt(8)
	s_waitcnt lgkmcnt(0)
	s_setprio 1
	s_barrier
	v_mfma_f32_16x16x32_bf16 v[62:65], v[146:149], v[188:191], v[62:65]
	v_mfma_f32_16x16x32_bf16 v[58:61], v[154:157], v[188:191], v[58:61]
	v_mfma_f32_16x16x32_bf16 v[54:57], v[146:149], v[196:199], v[54:57]
	v_mfma_f32_16x16x32_bf16 v[46:49], v[154:157], v[196:199], v[46:49]
	v_mfma_f32_16x16x32_bf16 v[38:41], v[146:149], v[204:207], v[38:41]
	v_mfma_f32_16x16x32_bf16 v[30:33], v[154:157], v[204:207], v[30:33]
	v_mfma_f32_16x16x32_bf16 v[22:25], v[146:149], v[212:215], v[22:25]
	v_mfma_f32_16x16x32_bf16 v[14:17], v[154:157], v[212:215], v[14:17]
	v_mfma_f32_16x16x32_bf16 v[62:65], v[150:153], v[192:195], v[62:65]
	v_mfma_f32_16x16x32_bf16 v[58:61], v[168:171], v[192:195], v[58:61]
	v_mfma_f32_16x16x32_bf16 v[54:57], v[150:153], v[200:203], v[54:57]
	v_mfma_f32_16x16x32_bf16 v[46:49], v[168:171], v[200:203], v[46:49]
	v_mfma_f32_16x16x32_bf16 v[38:41], v[150:153], v[208:211], v[38:41]
	v_mfma_f32_16x16x32_bf16 v[30:33], v[168:171], v[208:211], v[30:33]
	v_mfma_f32_16x16x32_bf16 v[22:25], v[150:153], v[218:221], v[22:25]
	v_mfma_f32_16x16x32_bf16 v[14:17], v[168:171], v[218:221], v[14:17]
	s_setprio 0
	s_setprio 1
	v_mfma_f32_16x16x32_bf16 v[50:53], v[172:175], v[188:191], v[50:53]
	v_mfma_f32_16x16x32_bf16 v[42:45], v[180:183], v[188:191], v[42:45]
	v_mfma_f32_16x16x32_bf16 v[34:37], v[172:175], v[196:199], v[34:37]
	v_mfma_f32_16x16x32_bf16 v[26:29], v[180:183], v[196:199], v[26:29]
	v_mfma_f32_16x16x32_bf16 v[18:21], v[172:175], v[204:207], v[18:21]
	v_mfma_f32_16x16x32_bf16 v[10:13], v[180:183], v[204:207], v[10:13]
	v_mfma_f32_16x16x32_bf16 v[6:9], v[172:175], v[212:215], v[6:9]
	v_mfma_f32_16x16x32_bf16 v[2:5], v[180:183], v[212:215], v[2:5]
	v_mfma_f32_16x16x32_bf16 v[50:53], v[176:179], v[192:195], v[50:53]
	v_mfma_f32_16x16x32_bf16 v[42:45], v[184:187], v[192:195], v[42:45]
	v_mfma_f32_16x16x32_bf16 v[34:37], v[176:179], v[200:203], v[34:37]
	v_mfma_f32_16x16x32_bf16 v[26:29], v[184:187], v[200:203], v[26:29]
	v_mfma_f32_16x16x32_bf16 v[18:21], v[176:179], v[208:211], v[18:21]
	v_mfma_f32_16x16x32_bf16 v[10:13], v[184:187], v[208:211], v[10:13]
	v_mfma_f32_16x16x32_bf16 v[6:9], v[176:179], v[218:221], v[6:9]
	v_mfma_f32_16x16x32_bf16 v[2:5], v[184:187], v[218:221], v[2:5]
	s_barrier
	s_setprio 0
	s_add_i32 s71, s71, 2
	s_add_u32 s38, s38, 0x100
	s_addc_u32 s39, s39, 0
	s_add_u32 s68, s68, 0x100
	s_addc_u32 s69, s69, 0
	s_cmp_gt_u32 s71, 61
	s_cbranch_scc0 .LBB0_292
	s_and_b64 vcc, exec, s[12:13]
	s_cbranch_vccnz .LBB0_300
	v_lshl_add_u32 v146, s0, 8, v1
	s_cmp_gt_u32 s54, 7
	s_mov_b64 s[38:39], -1
	s_cbranch_scc1 .LBB0_301

; #define PG8_STAGE(bufoff, gbase, voff) do { _Pragma("unroll") for (int _i = 0; _i < 2; ++_i) \
;         __builtin_amdgcn_global_load_lds((const unsigned*)((const char*)(gbase) + (voff)[_i]), (PG8_LAS unsigned*)(lds + (bufoff) + ldsw + _i * 8192), 16, 0, 0); } while (0)
; #define PG8_LDA(dst, b, h) do { _Pragma("unroll") for (int m = 0; m < 4; ++m) _Pragma("unroll") for (int k = 0; k < 2; ++k) dst[m][k] = *(const PG8_LAS bf16x8*)(lds + PG8_SA(b, h) + aoff + m * 2048 + k * 1024); } while (0)
; #define PG8_LDB(dst, b, h) do { _Pragma("unroll") for (int n = 0; n < 2; ++n) _Pragma("unroll") for (int k = 0; k < 2; ++k) dst[n][k] = *(const PG8_LAS bf16x8*)(lds + PG8_SB(b, h) + boff + n * 2048 + k * 1024); } while (0)
; #define PG8_MMA(ai, bj, At, Bt) do { __builtin_amdgcn_s_setprio(1); _Pragma("unroll") for (int m = 0; m < 4; ++m) _Pragma("unroll") for (int n = 0; n < 2; ++n) _Pragma("unroll") for (int k = 0; k < 2; ++k) \
;         acc[ai][bj][m][n] = __builtin_amdgcn_mfma_f32_16x16x32_bf16(Bt[n][k], At[m][k], acc[ai][bj][m][n], 0, 0, 0); __builtin_amdgcn_s_setprio(0); } while (0)
; #define PG8_WAIT_V(n) asm volatile("s_waitcnt vmcnt(" #n ")" ::: "memory")
; #define PG8_WAIT_L(n) asm volatile("s_waitcnt lgkmcnt(" #n ")" ::: "memory")
; template <class Epi, class Sched, bool ALIGN_EPI = false, bool SP2 = false>
; __device__ __forceinline__ void gemm_phase(PG8_LAS unsigned char* lds, const Gemm g, const Sched& S, const Epi& E) {
;     ...
;             const bool last = (t == nt - 2);
;             const char* a1 = cA + (size_t)(t + 1) * kstep;
;             const char* a2 = last ? nA : cA + (size_t)(t + 2) * kstep; const char* b2 = last ? nB : cB + (size_t)(t + 2) * kstep;
;             const char* a3 = a2 + kstep; const char* b3 = b2 + kstep;
;             if (last && has_next) S.a_ready(nxt);
;             if constexpr (SP2) {
;             PG8_LDB(B0, 0, 0); PG8_LDB(B1, 0, 1); PG8_SCHED; PG8_LDA(At, 0, 0); PG8_STAGE(PG8_SA(1, 1), a1 + hstep, voffA);
;             PG8_WAIT_V(8); PG8_WAIT_L(0); PG8_BAR; PG8_MMA(0, 0, At, B0); PG8_MMA(0, 1, At, B1); PG8_BAR; PG8_SCHED;
;             PG8_LDA(At, 0, 1); PG8_STAGE(PG8_SB(0, 0), b2, voffB); PG8_STAGE(PG8_SB(0, 1), b2 + hstep, voffB); PG8_STAGE(PG8_SA(0, 0), a2, voffA);
;             PG8_WAIT_V(8); PG8_WAIT_L(0); PG8_BAR; PG8_MMA(1, 0, At, B0); PG8_MMA(1, 1, At, B1); PG8_BAR; PG8_SCHED;
.LBB0_781:
	ds_read_b128 v[146:149], v152
	ds_read_b128 v[156:159], v152 offset:1024
	ds_read_b128 v[160:163], v152 offset:2048
	ds_read_b128 v[164:167], v152 offset:3072
	ds_read_b128 v[168:171], v153
	ds_read_b128 v[172:175], v153 offset:1024
	ds_read_b128 v[176:179], v153 offset:2048
	ds_read_b128 v[180:183], v153 offset:3072
	s_add_u32 s38, s36, 0xfff00080
	s_addc_u32 s39, s37, -1
	s_cmp_eq_u32 s56, 60
	s_cselect_b32 s41, s25, s39
	s_cselect_b32 s40, s31, s38
	s_cselect_b32 s39, s23, s55
	s_cselect_b32 s38, s35, s54
	v_lshl_add_u64 v[218:219], s[36:37], 0, v[138:139]
	s_add_i32 m0, s44, 0xc000
	ds_read_b128 v[184:187], v154
	ds_read_b128 v[188:191], v154 offset:1024
	ds_read_b128 v[192:195], v154 offset:2048
	ds_read_b128 v[196:199], v154 offset:3072
	ds_read_b128 v[200:203], v154 offset:4096
	ds_read_b128 v[204:207], v154 offset:5120
	ds_read_b128 v[208:211], v154 offset:6144
	ds_read_b128 v[212:215], v154 offset:7168
	global_load_lds_dwordx4 v[218:219], off
	v_lshl_add_u64 v[218:219], s[36:37], 0, v[140:141]
	s_add_i32 m0, s44, 0xe000
	s_nop 0
	global_load_lds_dwordx4 v[218:219], off
	s_waitcnt vmcnt(8)
	s_waitcnt lgkmcnt(0)
	s_setprio 1
	s_barrier
	v_mfma_f32_16x16x32_bf16 v[126:129], v[146:149], v[184:187], v[126:129]
	v_mfma_f32_16x16x32_bf16 v[122:125], v[160:163], v[184:187], v[122:125]
	v_mfma_f32_16x16x32_bf16 v[110:113], v[146:149], v[192:195], v[110:113]
	v_mfma_f32_16x16x32_bf16 v[106:109], v[160:163], v[192:195], v[106:109]
	v_mfma_f32_16x16x32_bf16 v[94:97], v[146:149], v[200:203], v[94:97]
	v_mfma_f32_16x16x32_bf16 v[90:93], v[160:163], v[200:203], v[90:93]
	v_mfma_f32_16x16x32_bf16 v[78:81], v[146:149], v[208:211], v[78:81]
	v_mfma_f32_16x16x32_bf16 v[74:77], v[160:163], v[208:211], v[74:77]
	v_mfma_f32_16x16x32_bf16 v[126:129], v[156:159], v[188:191], v[126:129]
	v_mfma_f32_16x16x32_bf16 v[122:125], v[164:167], v[188:191], v[122:125]
	v_mfma_f32_16x16x32_bf16 v[110:113], v[156:159], v[196:199], v[110:113]
	v_mfma_f32_16x16x32_bf16 v[106:109], v[164:167], v[196:199], v[106:109]
	v_mfma_f32_16x16x32_bf16 v[94:97], v[156:159], v[204:207], v[94:97]
	v_mfma_f32_16x16x32_bf16 v[90:93], v[164:167], v[204:207], v[90:93]
	v_mfma_f32_16x16x32_bf16 v[78:81], v[156:159], v[212:215], v[78:81]
	v_mfma_f32_16x16x32_bf16 v[74:77], v[164:167], v[212:215], v[74:77]
	s_setprio 0
	s_setprio 1
	v_mfma_f32_16x16x32_bf16 v[118:121], v[168:171], v[184:187], v[118:121]
	v_mfma_f32_16x16x32_bf16 v[114:117], v[176:179], v[184:187], v[114:117]
	v_mfma_f32_16x16x32_bf16 v[102:105], v[168:171], v[192:195], v[102:105]
	v_mfma_f32_16x16x32_bf16 v[98:101], v[176:179], v[192:195], v[98:101]
	v_mfma_f32_16x16x32_bf16 v[86:89], v[168:171], v[200:203], v[86:89]
	v_mfma_f32_16x16x32_bf16 v[82:85], v[176:179], v[200:203], v[82:85]
	v_mfma_f32_16x16x32_bf16 v[70:73], v[168:171], v[208:211], v[70:73]
	v_mfma_f32_16x16x32_bf16 v[66:69], v[176:179], v[208:211], v[66:69]
	v_mfma_f32_16x16x32_bf16 v[118:121], v[172:175], v[188:191], v[118:121]
	v_mfma_f32_16x16x32_bf16 v[114:117], v[180:183], v[188:191], v[114:117]
	v_mfma_f32_16x16x32_bf16 v[102:105], v[172:175], v[196:199], v[102:105]
	v_mfma_f32_16x16x32_bf16 v[98:101], v[180:183], v[196:199], v[98:101]
	v_mfma_f32_16x16x32_bf16 v[86:89], v[172:175], v[204:207], v[86:89]
	v_mfma_f32_16x16x32_bf16 v[82:85], v[180:183], v[204:207], v[82:85]
	v_mfma_f32_16x16x32_bf16 v[70:73], v[172:175], v[212:215], v[70:73]
	v_mfma_f32_16x16x32_bf16 v[66:69], v[180:183], v[212:215], v[66:69]
	s_barrier
	s_setprio 0
	s_add_i32 s57, s52, s33
	v_lshl_add_u64 v[218:219], s[38:39], 0, v[132:133]
	s_mov_b32 m0, s57
	ds_read_b128 v[184:187], v154 offset:16384
	ds_read_b128 v[188:191], v154 offset:17408
	ds_read_b128 v[192:195], v154 offset:18432
	ds_read_b128 v[196:199], v154 offset:19456
	ds_read_b128 v[200:203], v154 offset:20480
	ds_read_b128 v[204:207], v154 offset:21504
	ds_read_b128 v[208:211], v154 offset:22528
	ds_read_b128 v[212:215], v154 offset:23552
	global_load_lds_dwordx4 v[218:219], off
	s_add_i32 m0, s57, 0x2000
	s_add_u32 s58, s38, 0x100000
	v_lshl_add_u64 v[220:221], s[38:39], 0, v[136:137]
	s_addc_u32 s59, s39, 0
	s_add_i32 s57, s53, s33
	global_load_lds_dwordx4 v[220:221], off
	v_lshl_add_u64 v[222:223], s[58:59], 0, v[132:133]
	s_mov_b32 m0, s57
	v_lshl_add_u64 v[224:225], s[40:41], 0, v[134:135]
	global_load_lds_dwordx4 v[222:223], off
	v_lshl_add_u64 v[222:223], s[58:59], 0, v[136:137]
	s_add_i32 m0, s57, 0x2000
	s_nop 0
	global_load_lds_dwordx4 v[222:223], off
	v_lshl_add_u64 v[222:223], s[40:41], 0, v[130:131]
	s_mov_b32 m0, s44
	s_nop 0
	global_load_lds_dwordx4 v[222:223], off
	s_mov_b32 m0, s45
	s_nop 0
	global_load_lds_dwordx4 v[224:225], off
	s_waitcnt vmcnt(8)
	s_waitcnt lgkmcnt(0)
	s_setprio 1
	s_barrier
; #define PG8_STAGE(bufoff, gbase, voff) do { _Pragma("unroll") for (int _i = 0; _i < 2; ++_i) \
;         __builtin_amdgcn_global_load_lds((const unsigned*)((const char*)(gbase) + (voff)[_i]), (PG8_LAS unsigned*)(lds + (bufoff) + ldsw + _i * 8192), 16, 0, 0); } while (0)
; #define PG8_LDA(dst, b, h) do { _Pragma("unroll") for (int m = 0; m < 4; ++m) _Pragma("unroll") for (int k = 0; k < 2; ++k) dst[m][k] = *(const PG8_LAS bf16x8*)(lds + PG8_SA(b, h) + aoff + m * 2048 + k * 1024); } while (0)
; #define PG8_LDB(dst, b, h) do { _Pragma("unroll") for (int n = 0; n < 2; ++n) _Pragma("unroll") for (int k = 0; k < 2; ++k) dst[n][k] = *(const PG8_LAS bf16x8*)(lds + PG8_SB(b, h) + boff + n * 2048 + k * 1024); } while (0)
; #define PG8_MMA(ai, bj, At, Bt) do { __builtin_amdgcn_s_setprio(1); _Pragma("unroll") for (int m = 0; m < 4; ++m) _Pragma("unroll") for (int n = 0; n < 2; ++n) _Pragma("unroll") for (int k = 0; k < 2; ++k) \
;         acc[ai][bj][m][n] = __builtin_amdgcn_mfma_f32_16x16x32_bf16(Bt[n][k], At[m][k], acc[ai][bj][m][n], 0, 0, 0); __builtin_amdgcn_s_setprio(0); } while (0)
; #define PG8_WAIT_V(n) asm volatile("s_waitcnt vmcnt(" #n ")" ::: "memory")
; #define PG8_WAIT_L(n) asm volatile("s_waitcnt lgkmcnt(" #n ")" ::: "memory")
; #define PG8_BAR __builtin_amdgcn_s_barrier()
; #define PG8_SCHED __builtin_amdgcn_sched_barrier(0)
; template <class Epi, class Sched, bool ALIGN_EPI = false, bool SP2 = false>
; __device__ __forceinline__ void gemm_phase(PG8_LAS unsigned char* lds, const Gemm g, const Sched& S, const Epi& E) {
;     ...
;             PG8_WAIT_V(8); PG8_WAIT_L(0); PG8_BAR; PG8_MMA(1, 0, At, B0); PG8_MMA(1, 1, At, B1); PG8_BAR; PG8_SCHED;
;             PG8_LDB(B0, 1, 0); PG8_LDB(B1, 1, 1); PG8_SCHED; PG8_LDA(At, 1, 0); PG8_STAGE(PG8_SA(0, 1), a2 + hstep, voffA);
;             PG8_WAIT_V(8); PG8_WAIT_L(0); PG8_BAR; PG8_MMA(0, 0, At, B0); PG8_MMA(0, 1, At, B1); PG8_BAR; PG8_SCHED;
	v_mfma_f32_16x16x32_bf16 v[62:65], v[146:149], v[184:187], v[62:65]
	v_mfma_f32_16x16x32_bf16 v[58:61], v[160:163], v[184:187], v[58:61]
	v_mfma_f32_16x16x32_bf16 v[46:49], v[146:149], v[192:195], v[46:49]
	v_mfma_f32_16x16x32_bf16 v[42:45], v[160:163], v[192:195], v[42:45]
	v_mfma_f32_16x16x32_bf16 v[30:33], v[146:149], v[200:203], v[30:33]
	v_mfma_f32_16x16x32_bf16 v[26:29], v[160:163], v[200:203], v[26:29]
	v_mfma_f32_16x16x32_bf16 v[14:17], v[146:149], v[208:211], v[14:17]
	v_mfma_f32_16x16x32_bf16 v[10:13], v[160:163], v[208:211], v[10:13]
	v_mfma_f32_16x16x32_bf16 v[62:65], v[156:159], v[188:191], v[62:65]
	v_mfma_f32_16x16x32_bf16 v[58:61], v[164:167], v[188:191], v[58:61]
	v_mfma_f32_16x16x32_bf16 v[46:49], v[156:159], v[196:199], v[46:49]
	v_mfma_f32_16x16x32_bf16 v[42:45], v[164:167], v[196:199], v[42:45]
	v_mfma_f32_16x16x32_bf16 v[30:33], v[156:159], v[204:207], v[30:33]
	v_mfma_f32_16x16x32_bf16 v[26:29], v[164:167], v[204:207], v[26:29]
	v_mfma_f32_16x16x32_bf16 v[14:17], v[156:159], v[212:215], v[14:17]
	v_mfma_f32_16x16x32_bf16 v[10:13], v[164:167], v[212:215], v[10:13]
	s_setprio 0
	s_setprio 1
	v_mfma_f32_16x16x32_bf16 v[54:57], v[168:171], v[184:187], v[54:57]
	v_mfma_f32_16x16x32_bf16 v[50:53], v[176:179], v[184:187], v[50:53]
	v_mfma_f32_16x16x32_bf16 v[38:41], v[168:171], v[192:195], v[38:41]
	v_mfma_f32_16x16x32_bf16 v[34:37], v[176:179], v[192:195], v[34:37]
	v_mfma_f32_16x16x32_bf16 v[22:25], v[168:171], v[200:203], v[22:25]
	v_mfma_f32_16x16x32_bf16 v[18:21], v[176:179], v[200:203], v[18:21]
	v_mfma_f32_16x16x32_bf16 v[6:9], v[168:171], v[208:211], v[6:9]
	v_mfma_f32_16x16x32_bf16 v[2:5], v[176:179], v[208:211], v[2:5]
	v_mfma_f32_16x16x32_bf16 v[54:57], v[172:175], v[188:191], v[54:57]
	v_mfma_f32_16x16x32_bf16 v[50:53], v[180:183], v[188:191], v[50:53]
	v_mfma_f32_16x16x32_bf16 v[38:41], v[172:175], v[196:199], v[38:41]
	v_mfma_f32_16x16x32_bf16 v[34:37], v[180:183], v[196:199], v[34:37]
	v_mfma_f32_16x16x32_bf16 v[22:25], v[172:175], v[204:207], v[22:25]
	v_mfma_f32_16x16x32_bf16 v[18:21], v[180:183], v[204:207], v[18:21]
	v_mfma_f32_16x16x32_bf16 v[6:9], v[172:175], v[212:215], v[6:9]
	v_mfma_f32_16x16x32_bf16 v[2:5], v[180:183], v[212:215], v[2:5]
	s_barrier
	s_setprio 0
	s_add_i32 s57, 0, 0x18000
	s_add_i32 s58, 0, 0x1c000
	v_add_u32_e32 v164, s57, v150
	v_add_u32_e32 v180, s58, v150
	ds_read_b128 v[146:149], v164
	ds_read_b128 v[156:159], v164 offset:1024
	ds_read_b128 v[160:163], v164 offset:2048
	ds_read_b128 v[164:167], v164 offset:3072
	ds_read_b128 v[168:171], v180
	ds_read_b128 v[172:175], v180 offset:1024
	ds_read_b128 v[176:179], v180 offset:2048
	ds_read_b128 v[180:183], v180 offset:3072
	s_add_u32 s40, s40, 0x100000
	s_addc_u32 s41, s41, 0
	s_mov_b32 m0, s46
	v_lshl_add_u64 v[226:227], s[40:41], 0, v[130:131]
	ds_read_b128 v[184:187], v154 offset:32768
	ds_read_b128 v[188:191], v154 offset:33792
	ds_read_b128 v[192:195], v154 offset:34816
	ds_read_b128 v[196:199], v154 offset:35840
	ds_read_b128 v[200:203], v154 offset:36864
	ds_read_b128 v[204:207], v154 offset:37888
	ds_read_b128 v[208:211], v154 offset:38912
	ds_read_b128 v[212:215], v154 offset:39936
	global_load_lds_dwordx4 v[226:227], off
	v_lshl_add_u64 v[226:227], s[40:41], 0, v[134:135]
	s_mov_b32 m0, s47
	s_nop 0
	global_load_lds_dwordx4 v[226:227], off
	s_waitcnt vmcnt(8)
	s_waitcnt lgkmcnt(0)
	s_setprio 1
	s_barrier
	v_mfma_f32_16x16x32_bf16 v[126:129], v[146:149], v[184:187], v[126:129]
	v_mfma_f32_16x16x32_bf16 v[122:125], v[160:163], v[184:187], v[122:125]
	v_mfma_f32_16x16x32_bf16 v[110:113], v[146:149], v[192:195], v[110:113]
	v_mfma_f32_16x16x32_bf16 v[106:109], v[160:163], v[192:195], v[106:109]
	v_mfma_f32_16x16x32_bf16 v[94:97], v[146:149], v[200:203], v[94:97]
	v_mfma_f32_16x16x32_bf16 v[90:93], v[160:163], v[200:203], v[90:93]
	v_mfma_f32_16x16x32_bf16 v[78:81], v[146:149], v[208:211], v[78:81]
	v_mfma_f32_16x16x32_bf16 v[74:77], v[160:163], v[208:211], v[74:77]
	v_mfma_f32_16x16x32_bf16 v[126:129], v[156:159], v[188:191], v[126:129]
	v_mfma_f32_16x16x32_bf16 v[122:125], v[164:167], v[188:191], v[122:125]
	v_mfma_f32_16x16x32_bf16 v[110:113], v[156:159], v[196:199], v[110:113]
	v_mfma_f32_16x16x32_bf16 v[106:109], v[164:167], v[196:199], v[106:109]
	v_mfma_f32_16x16x32_bf16 v[94:97], v[156:159], v[204:207], v[94:97]
	v_mfma_f32_16x16x32_bf16 v[90:93], v[164:167], v[204:207], v[90:93]
	v_mfma_f32_16x16x32_bf16 v[78:81], v[156:159], v[212:215], v[78:81]
	v_mfma_f32_16x16x32_bf16 v[74:77], v[164:167], v[212:215], v[74:77]
	s_setprio 0
	s_setprio 1
	v_mfma_f32_16x16x32_bf16 v[118:121], v[168:171], v[184:187], v[118:121]
	v_mfma_f32_16x16x32_bf16 v[114:117], v[176:179], v[184:187], v[114:117]
	v_mfma_f32_16x16x32_bf16 v[102:105], v[168:171], v[192:195], v[102:105]
	v_mfma_f32_16x16x32_bf16 v[98:101], v[176:179], v[192:195], v[98:101]
	v_mfma_f32_16x16x32_bf16 v[86:89], v[168:171], v[200:203], v[86:89]
	v_mfma_f32_16x16x32_bf16 v[82:85], v[176:179], v[200:203], v[82:85]
	v_mfma_f32_16x16x32_bf16 v[70:73], v[168:171], v[208:211], v[70:73]
	v_mfma_f32_16x16x32_bf16 v[66:69], v[176:179], v[208:211], v[66:69]
	v_mfma_f32_16x16x32_bf16 v[118:121], v[172:175], v[188:191], v[118:121]
	v_mfma_f32_16x16x32_bf16 v[114:117], v[180:183], v[188:191], v[114:117]
	v_mfma_f32_16x16x32_bf16 v[102:105], v[172:175], v[196:199], v[102:105]
	v_mfma_f32_16x16x32_bf16 v[98:101], v[180:183], v[196:199], v[98:101]
	v_mfma_f32_16x16x32_bf16 v[86:89], v[172:175], v[204:207], v[86:89]
	v_mfma_f32_16x16x32_bf16 v[82:85], v[180:183], v[204:207], v[82:85]
	v_mfma_f32_16x16x32_bf16 v[70:73], v[172:175], v[212:215], v[70:73]
	v_mfma_f32_16x16x32_bf16 v[66:69], v[180:183], v[212:215], v[66:69]
	s_barrier
; #define PG8_STAGE(bufoff, gbase, voff) do { _Pragma("unroll") for (int _i = 0; _i < 2; ++_i) \
;         __builtin_amdgcn_global_load_lds((const unsigned*)((const char*)(gbase) + (voff)[_i]), (PG8_LAS unsigned*)(lds + (bufoff) + ldsw + _i * 8192), 16, 0, 0); } while (0)
; #define PG8_LDA(dst, b, h) do { _Pragma("unroll") for (int m = 0; m < 4; ++m) _Pragma("unroll") for (int k = 0; k < 2; ++k) dst[m][k] = *(const PG8_LAS bf16x8*)(lds + PG8_SA(b, h) + aoff + m * 2048 + k * 1024); } while (0)
; #define PG8_MMA(ai, bj, At, Bt) do { __builtin_amdgcn_s_setprio(1); _Pragma("unroll") for (int m = 0; m < 4; ++m) _Pragma("unroll") for (int n = 0; n < 2; ++n) _Pragma("unroll") for (int k = 0; k < 2; ++k) \
;         acc[ai][bj][m][n] = __builtin_amdgcn_mfma_f32_16x16x32_bf16(Bt[n][k], At[m][k], acc[ai][bj][m][n], 0, 0, 0); __builtin_amdgcn_s_setprio(0); } while (0)
; #define PG8_WAIT_V(n) asm volatile("s_waitcnt vmcnt(" #n ")" ::: "memory")
; #define PG8_WAIT_L(n) asm volatile("s_waitcnt lgkmcnt(" #n ")" ::: "memory")
; #define PG8_BAR __builtin_amdgcn_s_barrier()
; #define PG8_SCHED __builtin_amdgcn_sched_barrier(0)
; template <class Epi, class Sched, bool ALIGN_EPI = false, bool SP2 = false>
; __device__ __forceinline__ void gemm_phase(PG8_LAS unsigned char* lds, const Gemm g, const Sched& S, const Epi& E) {
;     ...
;             PG8_LDA(At, 1, 1); PG8_STAGE(PG8_SB(1, 0), b3, voffB); PG8_STAGE(PG8_SB(1, 1), b3 + hstep, voffB); PG8_STAGE(PG8_SA(1, 0), a3, voffA);
;             PG8_WAIT_V(8); PG8_WAIT_L(0); PG8_BAR; PG8_MMA(1, 0, At, B0); PG8_MMA(1, 1, At, B1); PG8_BAR; PG8_SCHED;
;     ...
;         }
;         if constexpr (ALIGN_EPI) { if (wr == 0) PG8_BAR; }
	s_setprio 0
	s_add_i32 s40, s57, s33
	v_lshl_add_u64 v[218:219], v[218:219], 0, s[14:15]
	s_mov_b32 m0, s40
	ds_read_b128 v[184:187], v154 offset:49152
	ds_read_b128 v[188:191], v154 offset:50176
	ds_read_b128 v[192:195], v154 offset:51200
	ds_read_b128 v[196:199], v154 offset:52224
	ds_read_b128 v[200:203], v154 offset:53248
	ds_read_b128 v[204:207], v154 offset:54272
	ds_read_b128 v[208:211], v154 offset:55296
	ds_read_b128 v[212:215], v154 offset:56320
	global_load_lds_dwordx4 v[218:219], off
	s_add_i32 m0, s40, 0x2000
	s_add_u32 s38, s38, 0x100080
	v_lshl_add_u64 v[218:219], v[220:221], 0, s[14:15]
	s_addc_u32 s39, s39, 0
	s_add_i32 s40, s58, s33
	global_load_lds_dwordx4 v[218:219], off
	v_lshl_add_u64 v[218:219], s[38:39], 0, v[132:133]
	s_mov_b32 m0, s40
	s_nop 0
	global_load_lds_dwordx4 v[218:219], off
	v_lshl_add_u64 v[218:219], s[38:39], 0, v[136:137]
	s_add_i32 m0, s40, 0x2000
	s_nop 0
	global_load_lds_dwordx4 v[218:219], off
	v_lshl_add_u64 v[218:219], v[222:223], 0, s[14:15]
	s_mov_b32 m0, s50
	s_nop 0
	global_load_lds_dwordx4 v[218:219], off
	v_lshl_add_u64 v[218:219], v[224:225], 0, s[14:15]
	s_mov_b32 m0, s51
	s_nop 0
	global_load_lds_dwordx4 v[218:219], off
	s_waitcnt vmcnt(8)
	s_waitcnt lgkmcnt(0)
	s_setprio 1
	s_barrier
	v_mfma_f32_16x16x32_bf16 v[62:65], v[146:149], v[184:187], v[62:65]
	v_mfma_f32_16x16x32_bf16 v[58:61], v[160:163], v[184:187], v[58:61]
	v_mfma_f32_16x16x32_bf16 v[46:49], v[146:149], v[192:195], v[46:49]
	v_mfma_f32_16x16x32_bf16 v[42:45], v[160:163], v[192:195], v[42:45]
	v_mfma_f32_16x16x32_bf16 v[30:33], v[146:149], v[200:203], v[30:33]
	v_mfma_f32_16x16x32_bf16 v[26:29], v[160:163], v[200:203], v[26:29]
	v_mfma_f32_16x16x32_bf16 v[14:17], v[146:149], v[208:211], v[14:17]
	v_mfma_f32_16x16x32_bf16 v[10:13], v[160:163], v[208:211], v[10:13]
	v_mfma_f32_16x16x32_bf16 v[62:65], v[156:159], v[188:191], v[62:65]
	v_mfma_f32_16x16x32_bf16 v[58:61], v[164:167], v[188:191], v[58:61]
	v_mfma_f32_16x16x32_bf16 v[46:49], v[156:159], v[196:199], v[46:49]
	v_mfma_f32_16x16x32_bf16 v[42:45], v[164:167], v[196:199], v[42:45]
	v_mfma_f32_16x16x32_bf16 v[30:33], v[156:159], v[204:207], v[30:33]
	v_mfma_f32_16x16x32_bf16 v[26:29], v[164:167], v[204:207], v[26:29]
	v_mfma_f32_16x16x32_bf16 v[14:17], v[156:159], v[212:215], v[14:17]
	v_mfma_f32_16x16x32_bf16 v[10:13], v[164:167], v[212:215], v[10:13]
	s_setprio 0
	s_setprio 1
	v_mfma_f32_16x16x32_bf16 v[54:57], v[168:171], v[184:187], v[54:57]
	v_mfma_f32_16x16x32_bf16 v[50:53], v[176:179], v[184:187], v[50:53]
	v_mfma_f32_16x16x32_bf16 v[38:41], v[168:171], v[192:195], v[38:41]
	v_mfma_f32_16x16x32_bf16 v[34:37], v[176:179], v[192:195], v[34:37]
	v_mfma_f32_16x16x32_bf16 v[22:25], v[168:171], v[200:203], v[22:25]
	v_mfma_f32_16x16x32_bf16 v[18:21], v[176:179], v[200:203], v[18:21]
	v_mfma_f32_16x16x32_bf16 v[6:9], v[168:171], v[208:211], v[6:9]
	v_mfma_f32_16x16x32_bf16 v[2:5], v[176:179], v[208:211], v[2:5]
	v_mfma_f32_16x16x32_bf16 v[54:57], v[172:175], v[188:191], v[54:57]
	v_mfma_f32_16x16x32_bf16 v[50:53], v[180:183], v[188:191], v[50:53]
	v_mfma_f32_16x16x32_bf16 v[38:41], v[172:175], v[196:199], v[38:41]
	v_mfma_f32_16x16x32_bf16 v[34:37], v[180:183], v[196:199], v[34:37]
	v_mfma_f32_16x16x32_bf16 v[22:25], v[172:175], v[204:207], v[22:25]
	v_mfma_f32_16x16x32_bf16 v[18:21], v[180:183], v[204:207], v[18:21]
	v_mfma_f32_16x16x32_bf16 v[6:9], v[172:175], v[212:215], v[6:9]
	v_mfma_f32_16x16x32_bf16 v[2:5], v[180:183], v[212:215], v[2:5]
	s_barrier
	s_setprio 0
	s_add_i32 s56, s56, 2
	s_add_u32 s36, s36, 0x100
	s_addc_u32 s37, s37, 0
	s_add_u32 s54, s54, 0x100
	s_addc_u32 s55, s55, 0
	s_cmp_gt_u32 s56, 61
	s_cbranch_scc0 .LBB0_781
	s_and_b64 vcc, exec, s[20:21]
	s_cbranch_vccz .LBB0_784
	s_barrier

; #define PG8_STAGE(bufoff, gbase, voff) do { _Pragma("unroll") for (int _i = 0; _i < 2; ++_i) \
;         __builtin_amdgcn_global_load_lds((const unsigned*)((const char*)(gbase) + (voff)[_i]), (PG8_LAS unsigned*)(lds + (bufoff) + ldsw + _i * 8192), 16, 0, 0); } while (0)
; #define PG8_LDA(dst, b, h) do { _Pragma("unroll") for (int m = 0; m < 4; ++m) _Pragma("unroll") for (int k = 0; k < 2; ++k) dst[m][k] = *(const PG8_LAS bf16x8*)(lds + PG8_SA(b, h) + aoff + m * 2048 + k * 1024); } while (0)
; #define PG8_LDB(dst, b, h) do { _Pragma("unroll") for (int n = 0; n < 2; ++n) _Pragma("unroll") for (int k = 0; k < 2; ++k) dst[n][k] = *(const PG8_LAS bf16x8*)(lds + PG8_SB(b, h) + boff + n * 2048 + k * 1024); } while (0)
; #define PG8_MMA(ai, bj, At, Bt) do { __builtin_amdgcn_s_setprio(1); _Pragma("unroll") for (int m = 0; m < 4; ++m) _Pragma("unroll") for (int n = 0; n < 2; ++n) _Pragma("unroll") for (int k = 0; k < 2; ++k) \
;         acc[ai][bj][m][n] = __builtin_amdgcn_mfma_f32_16x16x32_bf16(Bt[n][k], At[m][k], acc[ai][bj][m][n], 0, 0, 0); __builtin_amdgcn_s_setprio(0); } while (0)
; #define PG8_WAIT_V(n) asm volatile("s_waitcnt vmcnt(" #n ")" ::: "memory")
; #define PG8_WAIT_L(n) asm volatile("s_waitcnt lgkmcnt(" #n ")" ::: "memory")
; template <class Epi, class Sched, bool ALIGN_EPI = false, bool SP2 = false>
; __device__ __forceinline__ void gemm_phase(PG8_LAS unsigned char* lds, const Gemm g, const Sched& S, const Epi& E) {
;     ...
;             const bool last = (t == nt - 2);
;             const char* a1 = cA + (size_t)(t + 1) * kstep;
;             const char* a2 = last ? nA : cA + (size_t)(t + 2) * kstep; const char* b2 = last ? nB : cB + (size_t)(t + 2) * kstep;
;             const char* a3 = a2 + kstep; const char* b3 = b2 + kstep;
;             if (last && has_next) S.a_ready(nxt);
;             if constexpr (SP2) {
;             PG8_LDB(B0, 0, 0); PG8_LDB(B1, 0, 1); PG8_SCHED; PG8_LDA(At, 0, 0); PG8_STAGE(PG8_SA(1, 1), a1 + hstep, voffA);
;             PG8_WAIT_V(8); PG8_WAIT_L(0); PG8_BAR; PG8_MMA(0, 0, At, B0); PG8_MMA(0, 1, At, B1); PG8_BAR; PG8_SCHED;
;             PG8_LDA(At, 0, 1); PG8_STAGE(PG8_SB(0, 0), b2, voffB); PG8_STAGE(PG8_SB(0, 1), b2 + hstep, voffB); PG8_STAGE(PG8_SA(0, 0), a2, voffA);
;             PG8_WAIT_V(8); PG8_WAIT_L(0); PG8_BAR; PG8_MMA(1, 0, At, B0); PG8_MMA(1, 1, At, B1); PG8_BAR; PG8_SCHED;
.LBB0_992:
	ds_read_b128 v[154:157], v150
	ds_read_b128 v[158:161], v150 offset:1024
	ds_read_b128 v[162:165], v150 offset:2048
	ds_read_b128 v[166:169], v150 offset:3072
	ds_read_b128 v[170:173], v151
	ds_read_b128 v[174:177], v151 offset:1024
	ds_read_b128 v[178:181], v151 offset:2048
	ds_read_b128 v[182:185], v151 offset:3072
	s_add_u32 s42, s40, 0xfff00080
	s_addc_u32 s43, s41, -1
	s_cmp_eq_u32 s66, 60
	s_cselect_b32 s45, s31, s43
	s_cselect_b32 s44, s59, s42
	s_cselect_b32 s43, s29, s63
	s_cselect_b32 s42, s61, s62
	v_lshl_add_u64 v[146:147], s[40:41], 0, v[138:139]
	s_add_i32 m0, s39, 0xc000
	ds_read_b128 v[186:189], v152
	ds_read_b128 v[190:193], v152 offset:1024
	ds_read_b128 v[194:197], v152 offset:2048
	ds_read_b128 v[198:201], v152 offset:3072
	ds_read_b128 v[202:205], v152 offset:4096
	ds_read_b128 v[206:209], v152 offset:5120
	ds_read_b128 v[210:213], v152 offset:6144
	ds_read_b128 v[218:221], v152 offset:7168
	global_load_lds_dwordx4 v[146:147], off
	v_lshl_add_u64 v[146:147], s[40:41], 0, v[140:141]
	s_add_i32 m0, s39, 0xe000
	s_nop 0
	global_load_lds_dwordx4 v[146:147], off
	s_waitcnt vmcnt(8)
	s_waitcnt lgkmcnt(0)
	s_setprio 1
	s_barrier
	v_mfma_f32_16x16x32_bf16 v[126:129], v[154:157], v[186:189], v[126:129]
	v_mfma_f32_16x16x32_bf16 v[122:125], v[162:165], v[186:189], v[122:125]
	v_mfma_f32_16x16x32_bf16 v[114:117], v[154:157], v[194:197], v[114:117]
	v_mfma_f32_16x16x32_bf16 v[106:109], v[162:165], v[194:197], v[106:109]
	v_mfma_f32_16x16x32_bf16 v[98:101], v[154:157], v[202:205], v[98:101]
	v_mfma_f32_16x16x32_bf16 v[90:93], v[162:165], v[202:205], v[90:93]
	v_mfma_f32_16x16x32_bf16 v[82:85], v[154:157], v[210:213], v[82:85]
	v_mfma_f32_16x16x32_bf16 v[74:77], v[162:165], v[210:213], v[74:77]
	v_mfma_f32_16x16x32_bf16 v[126:129], v[158:161], v[190:193], v[126:129]
	v_mfma_f32_16x16x32_bf16 v[122:125], v[166:169], v[190:193], v[122:125]
	v_mfma_f32_16x16x32_bf16 v[114:117], v[158:161], v[198:201], v[114:117]
	v_mfma_f32_16x16x32_bf16 v[106:109], v[166:169], v[198:201], v[106:109]
	v_mfma_f32_16x16x32_bf16 v[98:101], v[158:161], v[206:209], v[98:101]
	v_mfma_f32_16x16x32_bf16 v[90:93], v[166:169], v[206:209], v[90:93]
	v_mfma_f32_16x16x32_bf16 v[82:85], v[158:161], v[218:221], v[82:85]
	v_mfma_f32_16x16x32_bf16 v[74:77], v[166:169], v[218:221], v[74:77]
	s_setprio 0
	s_setprio 1
	v_mfma_f32_16x16x32_bf16 v[118:121], v[170:173], v[186:189], v[118:121]
	v_mfma_f32_16x16x32_bf16 v[110:113], v[178:181], v[186:189], v[110:113]
	v_mfma_f32_16x16x32_bf16 v[102:105], v[170:173], v[194:197], v[102:105]
	v_mfma_f32_16x16x32_bf16 v[94:97], v[178:181], v[194:197], v[94:97]
	v_mfma_f32_16x16x32_bf16 v[86:89], v[170:173], v[202:205], v[86:89]
	v_mfma_f32_16x16x32_bf16 v[78:81], v[178:181], v[202:205], v[78:81]
	v_mfma_f32_16x16x32_bf16 v[70:73], v[170:173], v[210:213], v[70:73]
	v_mfma_f32_16x16x32_bf16 v[66:69], v[178:181], v[210:213], v[66:69]
	v_mfma_f32_16x16x32_bf16 v[118:121], v[174:177], v[190:193], v[118:121]
	v_mfma_f32_16x16x32_bf16 v[110:113], v[182:185], v[190:193], v[110:113]
	v_mfma_f32_16x16x32_bf16 v[102:105], v[174:177], v[198:201], v[102:105]
	v_mfma_f32_16x16x32_bf16 v[94:97], v[182:185], v[198:201], v[94:97]
	v_mfma_f32_16x16x32_bf16 v[86:89], v[174:177], v[206:209], v[86:89]
	v_mfma_f32_16x16x32_bf16 v[78:81], v[182:185], v[206:209], v[78:81]
	v_mfma_f32_16x16x32_bf16 v[70:73], v[174:177], v[218:221], v[70:73]
	v_mfma_f32_16x16x32_bf16 v[66:69], v[182:185], v[218:221], v[66:69]
	s_barrier
	s_setprio 0
	s_add_i32 s67, s52, s33
	v_lshl_add_u64 v[146:147], s[42:43], 0, v[132:133]
	s_mov_b32 m0, s67
	ds_read_b128 v[186:189], v152 offset:16384
	ds_read_b128 v[190:193], v152 offset:17408
	ds_read_b128 v[194:197], v152 offset:18432
	ds_read_b128 v[198:201], v152 offset:19456
	ds_read_b128 v[202:205], v152 offset:20480
	ds_read_b128 v[206:209], v152 offset:21504
	ds_read_b128 v[210:213], v152 offset:22528
	ds_read_b128 v[218:221], v152 offset:23552
	global_load_lds_dwordx4 v[146:147], off
	s_add_i32 m0, s67, 0x2000
	s_add_u32 s68, s42, 0x100000
	v_lshl_add_u64 v[214:215], s[42:43], 0, v[136:137]
	s_addc_u32 s69, s43, 0
	s_add_i32 s67, s53, s33
	global_load_lds_dwordx4 v[214:215], off
	v_lshl_add_u64 v[222:223], s[68:69], 0, v[132:133]
	s_mov_b32 m0, s67
	v_lshl_add_u64 v[224:225], s[44:45], 0, v[134:135]
	global_load_lds_dwordx4 v[222:223], off
	v_lshl_add_u64 v[222:223], s[68:69], 0, v[136:137]
	s_add_i32 m0, s67, 0x2000
	s_nop 0
	global_load_lds_dwordx4 v[222:223], off
	v_lshl_add_u64 v[222:223], s[44:45], 0, v[130:131]
	s_mov_b32 m0, s39
	s_nop 0
	global_load_lds_dwordx4 v[222:223], off
	s_mov_b32 m0, s46
	s_nop 0
	global_load_lds_dwordx4 v[224:225], off
	s_waitcnt vmcnt(8)
	s_waitcnt lgkmcnt(0)
	s_setprio 1
	s_barrier
; #define PG8_STAGE(bufoff, gbase, voff) do { _Pragma("unroll") for (int _i = 0; _i < 2; ++_i) \
;         __builtin_amdgcn_global_load_lds((const unsigned*)((const char*)(gbase) + (voff)[_i]), (PG8_LAS unsigned*)(lds + (bufoff) + ldsw + _i * 8192), 16, 0, 0); } while (0)
; #define PG8_LDA(dst, b, h) do { _Pragma("unroll") for (int m = 0; m < 4; ++m) _Pragma("unroll") for (int k = 0; k < 2; ++k) dst[m][k] = *(const PG8_LAS bf16x8*)(lds + PG8_SA(b, h) + aoff + m * 2048 + k * 1024); } while (0)
; #define PG8_LDB(dst, b, h) do { _Pragma("unroll") for (int n = 0; n < 2; ++n) _Pragma("unroll") for (int k = 0; k < 2; ++k) dst[n][k] = *(const PG8_LAS bf16x8*)(lds + PG8_SB(b, h) + boff + n * 2048 + k * 1024); } while (0)
; #define PG8_MMA(ai, bj, At, Bt) do { __builtin_amdgcn_s_setprio(1); _Pragma("unroll") for (int m = 0; m < 4; ++m) _Pragma("unroll") for (int n = 0; n < 2; ++n) _Pragma("unroll") for (int k = 0; k < 2; ++k) \
;         acc[ai][bj][m][n] = __builtin_amdgcn_mfma_f32_16x16x32_bf16(Bt[n][k], At[m][k], acc[ai][bj][m][n], 0, 0, 0); __builtin_amdgcn_s_setprio(0); } while (0)
; #define PG8_WAIT_V(n) asm volatile("s_waitcnt vmcnt(" #n ")" ::: "memory")
; #define PG8_WAIT_L(n) asm volatile("s_waitcnt lgkmcnt(" #n ")" ::: "memory")
; #define PG8_BAR __builtin_amdgcn_s_barrier()
; #define PG8_SCHED __builtin_amdgcn_sched_barrier(0)
; template <class Epi, class Sched, bool ALIGN_EPI = false, bool SP2 = false>
; __device__ __forceinline__ void gemm_phase(PG8_LAS unsigned char* lds, const Gemm g, const Sched& S, const Epi& E) {
;     ...
;             PG8_WAIT_V(8); PG8_WAIT_L(0); PG8_BAR; PG8_MMA(1, 0, At, B0); PG8_MMA(1, 1, At, B1); PG8_BAR; PG8_SCHED;
;             PG8_LDB(B0, 1, 0); PG8_LDB(B1, 1, 1); PG8_SCHED; PG8_LDA(At, 1, 0); PG8_STAGE(PG8_SA(0, 1), a2 + hstep, voffA);
;             PG8_WAIT_V(8); PG8_WAIT_L(0); PG8_BAR; PG8_MMA(0, 0, At, B0); PG8_MMA(0, 1, At, B1); PG8_BAR; PG8_SCHED;
	v_mfma_f32_16x16x32_bf16 v[62:65], v[154:157], v[186:189], v[62:65]
	v_mfma_f32_16x16x32_bf16 v[58:61], v[162:165], v[186:189], v[58:61]
	v_mfma_f32_16x16x32_bf16 v[50:53], v[154:157], v[194:197], v[50:53]
	v_mfma_f32_16x16x32_bf16 v[42:45], v[162:165], v[194:197], v[42:45]
	v_mfma_f32_16x16x32_bf16 v[34:37], v[154:157], v[202:205], v[34:37]
	v_mfma_f32_16x16x32_bf16 v[26:29], v[162:165], v[202:205], v[26:29]
	v_mfma_f32_16x16x32_bf16 v[18:21], v[154:157], v[210:213], v[18:21]
	v_mfma_f32_16x16x32_bf16 v[10:13], v[162:165], v[210:213], v[10:13]
	v_mfma_f32_16x16x32_bf16 v[62:65], v[158:161], v[190:193], v[62:65]
	v_mfma_f32_16x16x32_bf16 v[58:61], v[166:169], v[190:193], v[58:61]
	v_mfma_f32_16x16x32_bf16 v[50:53], v[158:161], v[198:201], v[50:53]
	v_mfma_f32_16x16x32_bf16 v[42:45], v[166:169], v[198:201], v[42:45]
	v_mfma_f32_16x16x32_bf16 v[34:37], v[158:161], v[206:209], v[34:37]
	v_mfma_f32_16x16x32_bf16 v[26:29], v[166:169], v[206:209], v[26:29]
	v_mfma_f32_16x16x32_bf16 v[18:21], v[158:161], v[218:221], v[18:21]
	v_mfma_f32_16x16x32_bf16 v[10:13], v[166:169], v[218:221], v[10:13]
	s_setprio 0
	s_setprio 1
	v_mfma_f32_16x16x32_bf16 v[54:57], v[170:173], v[186:189], v[54:57]
	v_mfma_f32_16x16x32_bf16 v[46:49], v[178:181], v[186:189], v[46:49]
	v_mfma_f32_16x16x32_bf16 v[38:41], v[170:173], v[194:197], v[38:41]
	v_mfma_f32_16x16x32_bf16 v[30:33], v[178:181], v[194:197], v[30:33]
	v_mfma_f32_16x16x32_bf16 v[22:25], v[170:173], v[202:205], v[22:25]
	v_mfma_f32_16x16x32_bf16 v[14:17], v[178:181], v[202:205], v[14:17]
	v_mfma_f32_16x16x32_bf16 v[6:9], v[170:173], v[210:213], v[6:9]
	v_mfma_f32_16x16x32_bf16 v[2:5], v[178:181], v[210:213], v[2:5]
	v_mfma_f32_16x16x32_bf16 v[54:57], v[174:177], v[190:193], v[54:57]
	v_mfma_f32_16x16x32_bf16 v[46:49], v[182:185], v[190:193], v[46:49]
	v_mfma_f32_16x16x32_bf16 v[38:41], v[174:177], v[198:201], v[38:41]
	v_mfma_f32_16x16x32_bf16 v[30:33], v[182:185], v[198:201], v[30:33]
	v_mfma_f32_16x16x32_bf16 v[22:25], v[174:177], v[206:209], v[22:25]
	v_mfma_f32_16x16x32_bf16 v[14:17], v[182:185], v[206:209], v[14:17]
	v_mfma_f32_16x16x32_bf16 v[6:9], v[174:177], v[218:221], v[6:9]
	v_mfma_f32_16x16x32_bf16 v[2:5], v[182:185], v[218:221], v[2:5]
	s_barrier
	s_setprio 0
	s_add_i32 s67, 0, 0x18000
	v_add_u32_e32 v153, s67, v148
	s_add_i32 s68, 0, 0x1c000
	ds_read_b128 v[154:157], v153
	ds_read_b128 v[158:161], v153 offset:1024
	ds_read_b128 v[162:165], v153 offset:2048
	ds_read_b128 v[166:169], v153 offset:3072
	v_add_u32_e32 v153, s68, v148
	ds_read_b128 v[170:173], v153
	ds_read_b128 v[174:177], v153 offset:1024
	ds_read_b128 v[178:181], v153 offset:2048
	ds_read_b128 v[182:185], v153 offset:3072
	s_add_u32 s44, s44, 0x100000
	s_addc_u32 s45, s45, 0
	s_mov_b32 m0, s47
	v_lshl_add_u64 v[226:227], s[44:45], 0, v[130:131]
	ds_read_b128 v[186:189], v152 offset:32768
	ds_read_b128 v[190:193], v152 offset:33792
	ds_read_b128 v[194:197], v152 offset:34816
	ds_read_b128 v[198:201], v152 offset:35840
	ds_read_b128 v[202:205], v152 offset:36864
	ds_read_b128 v[206:209], v152 offset:37888
	ds_read_b128 v[210:213], v152 offset:38912
	ds_read_b128 v[218:221], v152 offset:39936
	global_load_lds_dwordx4 v[226:227], off
	v_lshl_add_u64 v[226:227], s[44:45], 0, v[134:135]
	s_mov_b32 m0, s48
	s_nop 0
	global_load_lds_dwordx4 v[226:227], off
	s_waitcnt vmcnt(8)
	s_waitcnt lgkmcnt(0)
	s_setprio 1
	s_barrier
	v_mfma_f32_16x16x32_bf16 v[126:129], v[154:157], v[186:189], v[126:129]
	v_mfma_f32_16x16x32_bf16 v[122:125], v[162:165], v[186:189], v[122:125]
	v_mfma_f32_16x16x32_bf16 v[114:117], v[154:157], v[194:197], v[114:117]
	v_mfma_f32_16x16x32_bf16 v[106:109], v[162:165], v[194:197], v[106:109]
	v_mfma_f32_16x16x32_bf16 v[98:101], v[154:157], v[202:205], v[98:101]
	v_mfma_f32_16x16x32_bf16 v[90:93], v[162:165], v[202:205], v[90:93]
	v_mfma_f32_16x16x32_bf16 v[82:85], v[154:157], v[210:213], v[82:85]
	v_mfma_f32_16x16x32_bf16 v[74:77], v[162:165], v[210:213], v[74:77]
	v_mfma_f32_16x16x32_bf16 v[126:129], v[158:161], v[190:193], v[126:129]
	v_mfma_f32_16x16x32_bf16 v[122:125], v[166:169], v[190:193], v[122:125]
	v_mfma_f32_16x16x32_bf16 v[114:117], v[158:161], v[198:201], v[114:117]
	v_mfma_f32_16x16x32_bf16 v[106:109], v[166:169], v[198:201], v[106:109]
	v_mfma_f32_16x16x32_bf16 v[98:101], v[158:161], v[206:209], v[98:101]
	v_mfma_f32_16x16x32_bf16 v[90:93], v[166:169], v[206:209], v[90:93]
	v_mfma_f32_16x16x32_bf16 v[82:85], v[158:161], v[218:221], v[82:85]
	v_mfma_f32_16x16x32_bf16 v[74:77], v[166:169], v[218:221], v[74:77]
	s_setprio 0
	s_setprio 1
	v_mfma_f32_16x16x32_bf16 v[118:121], v[170:173], v[186:189], v[118:121]
	v_mfma_f32_16x16x32_bf16 v[110:113], v[178:181], v[186:189], v[110:113]
	v_mfma_f32_16x16x32_bf16 v[102:105], v[170:173], v[194:197], v[102:105]
	v_mfma_f32_16x16x32_bf16 v[94:97], v[178:181], v[194:197], v[94:97]
	v_mfma_f32_16x16x32_bf16 v[86:89], v[170:173], v[202:205], v[86:89]
	v_mfma_f32_16x16x32_bf16 v[78:81], v[178:181], v[202:205], v[78:81]
	v_mfma_f32_16x16x32_bf16 v[70:73], v[170:173], v[210:213], v[70:73]
	v_mfma_f32_16x16x32_bf16 v[66:69], v[178:181], v[210:213], v[66:69]
	v_mfma_f32_16x16x32_bf16 v[118:121], v[174:177], v[190:193], v[118:121]
	v_mfma_f32_16x16x32_bf16 v[110:113], v[182:185], v[190:193], v[110:113]
	v_mfma_f32_16x16x32_bf16 v[102:105], v[174:177], v[198:201], v[102:105]
	v_mfma_f32_16x16x32_bf16 v[94:97], v[182:185], v[198:201], v[94:97]
	v_mfma_f32_16x16x32_bf16 v[86:89], v[174:177], v[206:209], v[86:89]
	v_mfma_f32_16x16x32_bf16 v[78:81], v[182:185], v[206:209], v[78:81]
	v_mfma_f32_16x16x32_bf16 v[70:73], v[174:177], v[218:221], v[70:73]
	v_mfma_f32_16x16x32_bf16 v[66:69], v[182:185], v[218:221], v[66:69]
	s_barrier
; #define PG8_STAGE(bufoff, gbase, voff) do { _Pragma("unroll") for (int _i = 0; _i < 2; ++_i) \
;         __builtin_amdgcn_global_load_lds((const unsigned*)((const char*)(gbase) + (voff)[_i]), (PG8_LAS unsigned*)(lds + (bufoff) + ldsw + _i * 8192), 16, 0, 0); } while (0)
; #define PG8_LDA(dst, b, h) do { _Pragma("unroll") for (int m = 0; m < 4; ++m) _Pragma("unroll") for (int k = 0; k < 2; ++k) dst[m][k] = *(const PG8_LAS bf16x8*)(lds + PG8_SA(b, h) + aoff + m * 2048 + k * 1024); } while (0)
; #define PG8_MMA(ai, bj, At, Bt) do { __builtin_amdgcn_s_setprio(1); _Pragma("unroll") for (int m = 0; m < 4; ++m) _Pragma("unroll") for (int n = 0; n < 2; ++n) _Pragma("unroll") for (int k = 0; k < 2; ++k) \
;         acc[ai][bj][m][n] = __builtin_amdgcn_mfma_f32_16x16x32_bf16(Bt[n][k], At[m][k], acc[ai][bj][m][n], 0, 0, 0); __builtin_amdgcn_s_setprio(0); } while (0)
; #define PG8_WAIT_V(n) asm volatile("s_waitcnt vmcnt(" #n ")" ::: "memory")
; #define PG8_WAIT_L(n) asm volatile("s_waitcnt lgkmcnt(" #n ")" ::: "memory")
; #define PG8_BAR __builtin_amdgcn_s_barrier()
; #define PG8_SCHED __builtin_amdgcn_sched_barrier(0)
; template <class Epi, class Sched, bool ALIGN_EPI = false, bool SP2 = false>
; __device__ __forceinline__ void gemm_phase(PG8_LAS unsigned char* lds, const Gemm g, const Sched& S, const Epi& E) {
;     ...
;             PG8_LDA(At, 1, 1); PG8_STAGE(PG8_SB(1, 0), b3, voffB); PG8_STAGE(PG8_SB(1, 1), b3 + hstep, voffB); PG8_STAGE(PG8_SA(1, 0), a3, voffA);
;             PG8_WAIT_V(8); PG8_WAIT_L(0); PG8_BAR; PG8_MMA(1, 0, At, B0); PG8_MMA(1, 1, At, B1); PG8_BAR; PG8_SCHED;
;     ...
;         if constexpr (ALIGN_EPI) { if (wr == 0) PG8_BAR; }
	s_setprio 0
	s_add_i32 s44, s67, s33
	v_lshl_add_u64 v[146:147], v[146:147], 0, s[12:13]
	s_mov_b32 m0, s44
	ds_read_b128 v[186:189], v152 offset:49152
	ds_read_b128 v[190:193], v152 offset:50176
	ds_read_b128 v[194:197], v152 offset:51200
	ds_read_b128 v[198:201], v152 offset:52224
	ds_read_b128 v[202:205], v152 offset:53248
	ds_read_b128 v[206:209], v152 offset:54272
	ds_read_b128 v[210:213], v152 offset:55296
	ds_read_b128 v[218:221], v152 offset:56320
	global_load_lds_dwordx4 v[146:147], off
	s_add_i32 m0, s44, 0x2000
	s_add_u32 s42, s42, 0x100080
	v_lshl_add_u64 v[146:147], v[214:215], 0, s[12:13]
	s_addc_u32 s43, s43, 0
	s_add_i32 s44, s68, s33
	global_load_lds_dwordx4 v[146:147], off
	v_lshl_add_u64 v[146:147], s[42:43], 0, v[132:133]
	s_mov_b32 m0, s44
	s_nop 0
	global_load_lds_dwordx4 v[146:147], off
	v_lshl_add_u64 v[146:147], s[42:43], 0, v[136:137]
	s_add_i32 m0, s44, 0x2000
	s_nop 0
	global_load_lds_dwordx4 v[146:147], off
	v_lshl_add_u64 v[146:147], v[222:223], 0, s[12:13]
	s_mov_b32 m0, s50
	s_nop 0
	global_load_lds_dwordx4 v[146:147], off
	v_lshl_add_u64 v[146:147], v[224:225], 0, s[12:13]
	s_mov_b32 m0, s51
	s_nop 0
	global_load_lds_dwordx4 v[146:147], off
	s_waitcnt vmcnt(8)
	s_waitcnt lgkmcnt(0)
	s_setprio 1
	s_barrier
	v_mfma_f32_16x16x32_bf16 v[62:65], v[154:157], v[186:189], v[62:65]
	v_mfma_f32_16x16x32_bf16 v[58:61], v[162:165], v[186:189], v[58:61]
	v_mfma_f32_16x16x32_bf16 v[50:53], v[154:157], v[194:197], v[50:53]
	v_mfma_f32_16x16x32_bf16 v[42:45], v[162:165], v[194:197], v[42:45]
	v_mfma_f32_16x16x32_bf16 v[34:37], v[154:157], v[202:205], v[34:37]
	v_mfma_f32_16x16x32_bf16 v[26:29], v[162:165], v[202:205], v[26:29]
	v_mfma_f32_16x16x32_bf16 v[18:21], v[154:157], v[210:213], v[18:21]
	v_mfma_f32_16x16x32_bf16 v[10:13], v[162:165], v[210:213], v[10:13]
	v_mfma_f32_16x16x32_bf16 v[62:65], v[158:161], v[190:193], v[62:65]
	v_mfma_f32_16x16x32_bf16 v[58:61], v[166:169], v[190:193], v[58:61]
	v_mfma_f32_16x16x32_bf16 v[50:53], v[158:161], v[198:201], v[50:53]
	v_mfma_f32_16x16x32_bf16 v[42:45], v[166:169], v[198:201], v[42:45]
	v_mfma_f32_16x16x32_bf16 v[34:37], v[158:161], v[206:209], v[34:37]
	v_mfma_f32_16x16x32_bf16 v[26:29], v[166:169], v[206:209], v[26:29]
	v_mfma_f32_16x16x32_bf16 v[18:21], v[158:161], v[218:221], v[18:21]
	v_mfma_f32_16x16x32_bf16 v[10:13], v[166:169], v[218:221], v[10:13]
	s_setprio 0
	s_setprio 1
	v_mfma_f32_16x16x32_bf16 v[54:57], v[170:173], v[186:189], v[54:57]
	v_mfma_f32_16x16x32_bf16 v[46:49], v[178:181], v[186:189], v[46:49]
	v_mfma_f32_16x16x32_bf16 v[38:41], v[170:173], v[194:197], v[38:41]
	v_mfma_f32_16x16x32_bf16 v[30:33], v[178:181], v[194:197], v[30:33]
	v_mfma_f32_16x16x32_bf16 v[22:25], v[170:173], v[202:205], v[22:25]
	v_mfma_f32_16x16x32_bf16 v[14:17], v[178:181], v[202:205], v[14:17]
	v_mfma_f32_16x16x32_bf16 v[6:9], v[170:173], v[210:213], v[6:9]
	v_mfma_f32_16x16x32_bf16 v[2:5], v[178:181], v[210:213], v[2:5]
	v_mfma_f32_16x16x32_bf16 v[54:57], v[174:177], v[190:193], v[54:57]
	v_mfma_f32_16x16x32_bf16 v[46:49], v[182:185], v[190:193], v[46:49]
	v_mfma_f32_16x16x32_bf16 v[38:41], v[174:177], v[198:201], v[38:41]
	v_mfma_f32_16x16x32_bf16 v[30:33], v[182:185], v[198:201], v[30:33]
	v_mfma_f32_16x16x32_bf16 v[22:25], v[174:177], v[206:209], v[22:25]
	v_mfma_f32_16x16x32_bf16 v[14:17], v[182:185], v[206:209], v[14:17]
	v_mfma_f32_16x16x32_bf16 v[6:9], v[174:177], v[218:221], v[6:9]
	v_mfma_f32_16x16x32_bf16 v[2:5], v[182:185], v[218:221], v[2:5]
	s_barrier
	s_setprio 0
	s_add_i32 s66, s66, 2
	s_add_u32 s40, s40, 0x100
	s_addc_u32 s41, s41, 0
	s_add_u32 s62, s62, 0x100
	s_addc_u32 s63, s63, 0
	s_cmp_gt_u32 s66, 61
	s_cbranch_scc0 .LBB0_992
	s_and_b64 vcc, exec, s[14:15]
	s_cbranch_vccz .LBB0_995
	s_barrier

; #define PG8_STAGE(bufoff, gbase, voff) do { _Pragma("unroll") for (int _i = 0; _i < 2; ++_i) \
;         __builtin_amdgcn_global_load_lds((const unsigned*)((const char*)(gbase) + (voff)[_i]), (PG8_LAS unsigned*)(lds + (bufoff) + ldsw + _i * 8192), 16, 0, 0); } while (0)
; #define PG8_LDA(dst, b, h) do { _Pragma("unroll") for (int m = 0; m < 4; ++m) _Pragma("unroll") for (int k = 0; k < 2; ++k) dst[m][k] = *(const PG8_LAS bf16x8*)(lds + PG8_SA(b, h) + aoff + m * 2048 + k * 1024); } while (0)
; #define PG8_LDB(dst, b, h) do { _Pragma("unroll") for (int n = 0; n < 2; ++n) _Pragma("unroll") for (int k = 0; k < 2; ++k) dst[n][k] = *(const PG8_LAS bf16x8*)(lds + PG8_SB(b, h) + boff + n * 2048 + k * 1024); } while (0)
; #define PG8_MMA(ai, bj, At, Bt) do { __builtin_amdgcn_s_setprio(1); _Pragma("unroll") for (int m = 0; m < 4; ++m) _Pragma("unroll") for (int n = 0; n < 2; ++n) _Pragma("unroll") for (int k = 0; k < 2; ++k) \
;         acc[ai][bj][m][n] = __builtin_amdgcn_mfma_f32_16x16x32_bf16(Bt[n][k], At[m][k], acc[ai][bj][m][n], 0, 0, 0); __builtin_amdgcn_s_setprio(0); } while (0)
; #define PG8_WAIT_V(n) asm volatile("s_waitcnt vmcnt(" #n ")" ::: "memory")
; #define PG8_BAR __builtin_amdgcn_s_barrier()
; template <class Epi, class Sched, bool ALIGN_EPI = false, bool SP2 = false>
; __device__ __forceinline__ void gemm_phase(PG8_LAS unsigned char* lds, const Gemm g, const Sched& S, const Epi& E) {
;     ...
;         for (int t = 0; t < nt; t += 2) {
;             const bool last = (t == nt - 2);
;             const char* a1 = cA + (size_t)(t + 1) * kstep;
;             const char* a2 = last ? nA : cA + (size_t)(t + 2) * kstep; const char* b2 = last ? nB : cB + (size_t)(t + 2) * kstep;
;             const char* a3 = a2 + kstep; const char* b3 = b2 + kstep;
;             if (last && has_next) S.a_ready(nxt);
;             if constexpr (SP2) {
;             PG8_LDB(B0, 0, 0); PG8_LDB(B1, 0, 1); PG8_SCHED; PG8_LDA(At, 0, 0); PG8_STAGE(PG8_SA(1, 1), a1 + hstep, voffA);
;             PG8_WAIT_V(8); PG8_WAIT_L(0); PG8_BAR; PG8_MMA(0, 0, At, B0); PG8_MMA(0, 1, At, B1); PG8_BAR; PG8_SCHED;
;             PG8_LDA(At, 0, 1); PG8_STAGE(PG8_SB(0, 0), b2, voffB); PG8_STAGE(PG8_SB(0, 1), b2 + hstep, voffB); PG8_STAGE(PG8_SA(0, 0), a2, voffA);
;             PG8_WAIT_V(8); PG8_WAIT_L(0); PG8_BAR; PG8_MMA(1, 0, At, B0); PG8_MMA(1, 1, At, B1); PG8_BAR; PG8_SCHED;
.LBB0_1089:
	ds_read_b128 v[146:149], v152
	ds_read_b128 v[156:159], v152 offset:1024
	ds_read_b128 v[160:163], v152 offset:2048
	ds_read_b128 v[164:167], v152 offset:3072
	ds_read_b128 v[168:171], v153
	ds_read_b128 v[172:175], v153 offset:1024
	ds_read_b128 v[176:179], v153 offset:2048
	ds_read_b128 v[180:183], v153 offset:3072
	s_add_u32 s38, s36, 0xffc00080
	s_addc_u32 s39, s37, -1
	s_cmpk_eq_i32 s54, 0xfc
	s_cselect_b32 s41, s25, s39
	s_cselect_b32 s40, s31, s38
	s_cselect_b32 s39, s23, s53
	s_cselect_b32 s38, s35, s52
	v_lshl_add_u64 v[218:219], s[36:37], 0, v[138:139]
	s_add_i32 m0, s42, 0xc000
	ds_read_b128 v[184:187], v154
	ds_read_b128 v[188:191], v154 offset:1024
	ds_read_b128 v[192:195], v154 offset:2048
	ds_read_b128 v[196:199], v154 offset:3072
	ds_read_b128 v[200:203], v154 offset:4096
	ds_read_b128 v[204:207], v154 offset:5120
	ds_read_b128 v[208:211], v154 offset:6144
	ds_read_b128 v[212:215], v154 offset:7168
	global_load_lds_dwordx4 v[218:219], off
	v_lshl_add_u64 v[218:219], s[36:37], 0, v[140:141]
	s_add_i32 m0, s42, 0xe000
	s_nop 0
	global_load_lds_dwordx4 v[218:219], off
	s_waitcnt vmcnt(8)
	s_waitcnt lgkmcnt(0)
	s_setprio 1
	s_barrier
	v_mfma_f32_16x16x32_bf16 v[126:129], v[146:149], v[184:187], v[126:129]
	v_mfma_f32_16x16x32_bf16 v[122:125], v[160:163], v[184:187], v[122:125]
	v_mfma_f32_16x16x32_bf16 v[110:113], v[146:149], v[192:195], v[110:113]
	v_mfma_f32_16x16x32_bf16 v[106:109], v[160:163], v[192:195], v[106:109]
	v_mfma_f32_16x16x32_bf16 v[94:97], v[146:149], v[200:203], v[94:97]
	v_mfma_f32_16x16x32_bf16 v[90:93], v[160:163], v[200:203], v[90:93]
	v_mfma_f32_16x16x32_bf16 v[78:81], v[146:149], v[208:211], v[78:81]
	v_mfma_f32_16x16x32_bf16 v[74:77], v[160:163], v[208:211], v[74:77]
	v_mfma_f32_16x16x32_bf16 v[126:129], v[156:159], v[188:191], v[126:129]
	v_mfma_f32_16x16x32_bf16 v[122:125], v[164:167], v[188:191], v[122:125]
	v_mfma_f32_16x16x32_bf16 v[110:113], v[156:159], v[196:199], v[110:113]
	v_mfma_f32_16x16x32_bf16 v[106:109], v[164:167], v[196:199], v[106:109]
	v_mfma_f32_16x16x32_bf16 v[94:97], v[156:159], v[204:207], v[94:97]
	v_mfma_f32_16x16x32_bf16 v[90:93], v[164:167], v[204:207], v[90:93]
	v_mfma_f32_16x16x32_bf16 v[78:81], v[156:159], v[212:215], v[78:81]
	v_mfma_f32_16x16x32_bf16 v[74:77], v[164:167], v[212:215], v[74:77]
	s_setprio 0
	s_setprio 1
	v_mfma_f32_16x16x32_bf16 v[118:121], v[168:171], v[184:187], v[118:121]
	v_mfma_f32_16x16x32_bf16 v[114:117], v[176:179], v[184:187], v[114:117]
	v_mfma_f32_16x16x32_bf16 v[102:105], v[168:171], v[192:195], v[102:105]
	v_mfma_f32_16x16x32_bf16 v[98:101], v[176:179], v[192:195], v[98:101]
	v_mfma_f32_16x16x32_bf16 v[86:89], v[168:171], v[200:203], v[86:89]
	v_mfma_f32_16x16x32_bf16 v[82:85], v[176:179], v[200:203], v[82:85]
	v_mfma_f32_16x16x32_bf16 v[70:73], v[168:171], v[208:211], v[70:73]
	v_mfma_f32_16x16x32_bf16 v[66:69], v[176:179], v[208:211], v[66:69]
	v_mfma_f32_16x16x32_bf16 v[118:121], v[172:175], v[188:191], v[118:121]
	v_mfma_f32_16x16x32_bf16 v[114:117], v[180:183], v[188:191], v[114:117]
	v_mfma_f32_16x16x32_bf16 v[102:105], v[172:175], v[196:199], v[102:105]
	v_mfma_f32_16x16x32_bf16 v[98:101], v[180:183], v[196:199], v[98:101]
	v_mfma_f32_16x16x32_bf16 v[86:89], v[172:175], v[204:207], v[86:89]
	v_mfma_f32_16x16x32_bf16 v[82:85], v[180:183], v[204:207], v[82:85]
	v_mfma_f32_16x16x32_bf16 v[70:73], v[172:175], v[212:215], v[70:73]
	v_mfma_f32_16x16x32_bf16 v[66:69], v[180:183], v[212:215], v[66:69]
	s_barrier
	s_setprio 0
	s_add_i32 s55, s50, s33
	v_lshl_add_u64 v[218:219], s[38:39], 0, v[132:133]
	s_mov_b32 m0, s55
	ds_read_b128 v[184:187], v154 offset:16384
	ds_read_b128 v[188:191], v154 offset:17408
	ds_read_b128 v[192:195], v154 offset:18432
	ds_read_b128 v[196:199], v154 offset:19456
	ds_read_b128 v[200:203], v154 offset:20480
	ds_read_b128 v[204:207], v154 offset:21504
	ds_read_b128 v[208:211], v154 offset:22528
	ds_read_b128 v[212:215], v154 offset:23552
	global_load_lds_dwordx4 v[218:219], off
	s_add_i32 m0, s55, 0x2000
	s_add_u32 s56, s38, 0x400000
	v_lshl_add_u64 v[220:221], s[38:39], 0, v[136:137]
	s_addc_u32 s57, s39, 0
	s_add_i32 s55, s51, s33
	global_load_lds_dwordx4 v[220:221], off
	v_lshl_add_u64 v[222:223], s[56:57], 0, v[132:133]
	s_mov_b32 m0, s55
	v_lshl_add_u64 v[224:225], s[40:41], 0, v[134:135]
	global_load_lds_dwordx4 v[222:223], off
	v_lshl_add_u64 v[222:223], s[56:57], 0, v[136:137]
	s_add_i32 m0, s55, 0x2000
	s_nop 0
	global_load_lds_dwordx4 v[222:223], off
	v_lshl_add_u64 v[222:223], s[40:41], 0, v[130:131]
	s_mov_b32 m0, s42
	s_nop 0
	global_load_lds_dwordx4 v[222:223], off
	s_mov_b32 m0, s43
	s_nop 0
	global_load_lds_dwordx4 v[224:225], off
	s_waitcnt vmcnt(8)
	s_waitcnt lgkmcnt(0)
	s_setprio 1
	s_barrier
; #define PG8_STAGE(bufoff, gbase, voff) do { _Pragma("unroll") for (int _i = 0; _i < 2; ++_i) \
;         __builtin_amdgcn_global_load_lds((const unsigned*)((const char*)(gbase) + (voff)[_i]), (PG8_LAS unsigned*)(lds + (bufoff) + ldsw + _i * 8192), 16, 0, 0); } while (0)
; #define PG8_LDA(dst, b, h) do { _Pragma("unroll") for (int m = 0; m < 4; ++m) _Pragma("unroll") for (int k = 0; k < 2; ++k) dst[m][k] = *(const PG8_LAS bf16x8*)(lds + PG8_SA(b, h) + aoff + m * 2048 + k * 1024); } while (0)
; #define PG8_LDB(dst, b, h) do { _Pragma("unroll") for (int n = 0; n < 2; ++n) _Pragma("unroll") for (int k = 0; k < 2; ++k) dst[n][k] = *(const PG8_LAS bf16x8*)(lds + PG8_SB(b, h) + boff + n * 2048 + k * 1024); } while (0)
; #define PG8_MMA(ai, bj, At, Bt) do { __builtin_amdgcn_s_setprio(1); _Pragma("unroll") for (int m = 0; m < 4; ++m) _Pragma("unroll") for (int n = 0; n < 2; ++n) _Pragma("unroll") for (int k = 0; k < 2; ++k) \
;         acc[ai][bj][m][n] = __builtin_amdgcn_mfma_f32_16x16x32_bf16(Bt[n][k], At[m][k], acc[ai][bj][m][n], 0, 0, 0); __builtin_amdgcn_s_setprio(0); } while (0)
; #define PG8_WAIT_V(n) asm volatile("s_waitcnt vmcnt(" #n ")" ::: "memory")
; #define PG8_WAIT_L(n) asm volatile("s_waitcnt lgkmcnt(" #n ")" ::: "memory")
; #define PG8_BAR __builtin_amdgcn_s_barrier()
; #define PG8_SCHED __builtin_amdgcn_sched_barrier(0)
; template <class Epi, class Sched, bool ALIGN_EPI = false, bool SP2 = false>
; __device__ __forceinline__ void gemm_phase(PG8_LAS unsigned char* lds, const Gemm g, const Sched& S, const Epi& E) {
;     ...
;             PG8_WAIT_V(8); PG8_WAIT_L(0); PG8_BAR; PG8_MMA(1, 0, At, B0); PG8_MMA(1, 1, At, B1); PG8_BAR; PG8_SCHED;
;             PG8_LDB(B0, 1, 0); PG8_LDB(B1, 1, 1); PG8_SCHED; PG8_LDA(At, 1, 0); PG8_STAGE(PG8_SA(0, 1), a2 + hstep, voffA);
;             PG8_WAIT_V(8); PG8_WAIT_L(0); PG8_BAR; PG8_MMA(0, 0, At, B0); PG8_MMA(0, 1, At, B1); PG8_BAR; PG8_SCHED;
	v_mfma_f32_16x16x32_bf16 v[62:65], v[146:149], v[184:187], v[62:65]
	v_mfma_f32_16x16x32_bf16 v[58:61], v[160:163], v[184:187], v[58:61]
	v_mfma_f32_16x16x32_bf16 v[46:49], v[146:149], v[192:195], v[46:49]
	v_mfma_f32_16x16x32_bf16 v[42:45], v[160:163], v[192:195], v[42:45]
	v_mfma_f32_16x16x32_bf16 v[30:33], v[146:149], v[200:203], v[30:33]
	v_mfma_f32_16x16x32_bf16 v[26:29], v[160:163], v[200:203], v[26:29]
	v_mfma_f32_16x16x32_bf16 v[14:17], v[146:149], v[208:211], v[14:17]
	v_mfma_f32_16x16x32_bf16 v[10:13], v[160:163], v[208:211], v[10:13]
	v_mfma_f32_16x16x32_bf16 v[62:65], v[156:159], v[188:191], v[62:65]
	v_mfma_f32_16x16x32_bf16 v[58:61], v[164:167], v[188:191], v[58:61]
	v_mfma_f32_16x16x32_bf16 v[46:49], v[156:159], v[196:199], v[46:49]
	v_mfma_f32_16x16x32_bf16 v[42:45], v[164:167], v[196:199], v[42:45]
	v_mfma_f32_16x16x32_bf16 v[30:33], v[156:159], v[204:207], v[30:33]
	v_mfma_f32_16x16x32_bf16 v[26:29], v[164:167], v[204:207], v[26:29]
	v_mfma_f32_16x16x32_bf16 v[14:17], v[156:159], v[212:215], v[14:17]
	v_mfma_f32_16x16x32_bf16 v[10:13], v[164:167], v[212:215], v[10:13]
	s_setprio 0
	s_setprio 1
	v_mfma_f32_16x16x32_bf16 v[54:57], v[168:171], v[184:187], v[54:57]
	v_mfma_f32_16x16x32_bf16 v[50:53], v[176:179], v[184:187], v[50:53]
	v_mfma_f32_16x16x32_bf16 v[38:41], v[168:171], v[192:195], v[38:41]
	v_mfma_f32_16x16x32_bf16 v[34:37], v[176:179], v[192:195], v[34:37]
	v_mfma_f32_16x16x32_bf16 v[22:25], v[168:171], v[200:203], v[22:25]
	v_mfma_f32_16x16x32_bf16 v[18:21], v[176:179], v[200:203], v[18:21]
	v_mfma_f32_16x16x32_bf16 v[6:9], v[168:171], v[208:211], v[6:9]
	v_mfma_f32_16x16x32_bf16 v[2:5], v[176:179], v[208:211], v[2:5]
	v_mfma_f32_16x16x32_bf16 v[54:57], v[172:175], v[188:191], v[54:57]
	v_mfma_f32_16x16x32_bf16 v[50:53], v[180:183], v[188:191], v[50:53]
	v_mfma_f32_16x16x32_bf16 v[38:41], v[172:175], v[196:199], v[38:41]
	v_mfma_f32_16x16x32_bf16 v[34:37], v[180:183], v[196:199], v[34:37]
	v_mfma_f32_16x16x32_bf16 v[22:25], v[172:175], v[204:207], v[22:25]
	v_mfma_f32_16x16x32_bf16 v[18:21], v[180:183], v[204:207], v[18:21]
	v_mfma_f32_16x16x32_bf16 v[6:9], v[172:175], v[212:215], v[6:9]
	v_mfma_f32_16x16x32_bf16 v[2:5], v[180:183], v[212:215], v[2:5]
	s_barrier
	s_setprio 0
	s_add_i32 s55, 0, 0x18000
	s_add_i32 s56, 0, 0x1c000
	v_add_u32_e32 v164, s55, v150
	v_add_u32_e32 v180, s56, v150
	ds_read_b128 v[146:149], v164
	ds_read_b128 v[156:159], v164 offset:1024
	ds_read_b128 v[160:163], v164 offset:2048
	ds_read_b128 v[164:167], v164 offset:3072
	ds_read_b128 v[168:171], v180
	ds_read_b128 v[172:175], v180 offset:1024
	ds_read_b128 v[176:179], v180 offset:2048
	ds_read_b128 v[180:183], v180 offset:3072
	s_add_u32 s40, s40, 0x400000
	s_addc_u32 s41, s41, 0
	s_mov_b32 m0, s44
	v_lshl_add_u64 v[226:227], s[40:41], 0, v[130:131]
	ds_read_b128 v[184:187], v154 offset:32768
	ds_read_b128 v[188:191], v154 offset:33792
	ds_read_b128 v[192:195], v154 offset:34816
	ds_read_b128 v[196:199], v154 offset:35840
	ds_read_b128 v[200:203], v154 offset:36864
	ds_read_b128 v[204:207], v154 offset:37888
	ds_read_b128 v[208:211], v154 offset:38912
	ds_read_b128 v[212:215], v154 offset:39936
	global_load_lds_dwordx4 v[226:227], off
	v_lshl_add_u64 v[226:227], s[40:41], 0, v[134:135]
	s_mov_b32 m0, s45
	s_nop 0
	global_load_lds_dwordx4 v[226:227], off
	s_waitcnt vmcnt(8)
	s_waitcnt lgkmcnt(0)
	s_setprio 1
	s_barrier
	v_mfma_f32_16x16x32_bf16 v[126:129], v[146:149], v[184:187], v[126:129]
	v_mfma_f32_16x16x32_bf16 v[122:125], v[160:163], v[184:187], v[122:125]
	v_mfma_f32_16x16x32_bf16 v[110:113], v[146:149], v[192:195], v[110:113]
	v_mfma_f32_16x16x32_bf16 v[106:109], v[160:163], v[192:195], v[106:109]
	v_mfma_f32_16x16x32_bf16 v[94:97], v[146:149], v[200:203], v[94:97]
	v_mfma_f32_16x16x32_bf16 v[90:93], v[160:163], v[200:203], v[90:93]
	v_mfma_f32_16x16x32_bf16 v[78:81], v[146:149], v[208:211], v[78:81]
	v_mfma_f32_16x16x32_bf16 v[74:77], v[160:163], v[208:211], v[74:77]
	v_mfma_f32_16x16x32_bf16 v[126:129], v[156:159], v[188:191], v[126:129]
	v_mfma_f32_16x16x32_bf16 v[122:125], v[164:167], v[188:191], v[122:125]
	v_mfma_f32_16x16x32_bf16 v[110:113], v[156:159], v[196:199], v[110:113]
	v_mfma_f32_16x16x32_bf16 v[106:109], v[164:167], v[196:199], v[106:109]
	v_mfma_f32_16x16x32_bf16 v[94:97], v[156:159], v[204:207], v[94:97]
	v_mfma_f32_16x16x32_bf16 v[90:93], v[164:167], v[204:207], v[90:93]
	v_mfma_f32_16x16x32_bf16 v[78:81], v[156:159], v[212:215], v[78:81]
	v_mfma_f32_16x16x32_bf16 v[74:77], v[164:167], v[212:215], v[74:77]
	s_setprio 0
	s_setprio 1
	v_mfma_f32_16x16x32_bf16 v[118:121], v[168:171], v[184:187], v[118:121]
	v_mfma_f32_16x16x32_bf16 v[114:117], v[176:179], v[184:187], v[114:117]
	v_mfma_f32_16x16x32_bf16 v[102:105], v[168:171], v[192:195], v[102:105]
	v_mfma_f32_16x16x32_bf16 v[98:101], v[176:179], v[192:195], v[98:101]
	v_mfma_f32_16x16x32_bf16 v[86:89], v[168:171], v[200:203], v[86:89]
	v_mfma_f32_16x16x32_bf16 v[82:85], v[176:179], v[200:203], v[82:85]
	v_mfma_f32_16x16x32_bf16 v[70:73], v[168:171], v[208:211], v[70:73]
	v_mfma_f32_16x16x32_bf16 v[66:69], v[176:179], v[208:211], v[66:69]
	v_mfma_f32_16x16x32_bf16 v[118:121], v[172:175], v[188:191], v[118:121]
	v_mfma_f32_16x16x32_bf16 v[114:117], v[180:183], v[188:191], v[114:117]
	v_mfma_f32_16x16x32_bf16 v[102:105], v[172:175], v[196:199], v[102:105]
	v_mfma_f32_16x16x32_bf16 v[98:101], v[180:183], v[196:199], v[98:101]
	v_mfma_f32_16x16x32_bf16 v[86:89], v[172:175], v[204:207], v[86:89]
	v_mfma_f32_16x16x32_bf16 v[82:85], v[180:183], v[204:207], v[82:85]
	v_mfma_f32_16x16x32_bf16 v[70:73], v[172:175], v[212:215], v[70:73]
	v_mfma_f32_16x16x32_bf16 v[66:69], v[180:183], v[212:215], v[66:69]
	s_barrier
; #define PG8_STAGE(bufoff, gbase, voff) do { _Pragma("unroll") for (int _i = 0; _i < 2; ++_i) \
;         __builtin_amdgcn_global_load_lds((const unsigned*)((const char*)(gbase) + (voff)[_i]), (PG8_LAS unsigned*)(lds + (bufoff) + ldsw + _i * 8192), 16, 0, 0); } while (0)
; #define PG8_LDA(dst, b, h) do { _Pragma("unroll") for (int m = 0; m < 4; ++m) _Pragma("unroll") for (int k = 0; k < 2; ++k) dst[m][k] = *(const PG8_LAS bf16x8*)(lds + PG8_SA(b, h) + aoff + m * 2048 + k * 1024); } while (0)
; #define PG8_MMA(ai, bj, At, Bt) do { __builtin_amdgcn_s_setprio(1); _Pragma("unroll") for (int m = 0; m < 4; ++m) _Pragma("unroll") for (int n = 0; n < 2; ++n) _Pragma("unroll") for (int k = 0; k < 2; ++k) \
;         acc[ai][bj][m][n] = __builtin_amdgcn_mfma_f32_16x16x32_bf16(Bt[n][k], At[m][k], acc[ai][bj][m][n], 0, 0, 0); __builtin_amdgcn_s_setprio(0); } while (0)
; #define PG8_WAIT_V(n) asm volatile("s_waitcnt vmcnt(" #n ")" ::: "memory")
; #define PG8_WAIT_L(n) asm volatile("s_waitcnt lgkmcnt(" #n ")" ::: "memory")
; #define PG8_BAR __builtin_amdgcn_s_barrier()
; #define PG8_SCHED __builtin_amdgcn_sched_barrier(0)
; template <class Epi, class Sched, bool ALIGN_EPI = false, bool SP2 = false>
; __device__ __forceinline__ void gemm_phase(PG8_LAS unsigned char* lds, const Gemm g, const Sched& S, const Epi& E) {
;     ...
;             PG8_LDA(At, 1, 1); PG8_STAGE(PG8_SB(1, 0), b3, voffB); PG8_STAGE(PG8_SB(1, 1), b3 + hstep, voffB); PG8_STAGE(PG8_SA(1, 0), a3, voffA);
;             PG8_WAIT_V(8); PG8_WAIT_L(0); PG8_BAR; PG8_MMA(1, 0, At, B0); PG8_MMA(1, 1, At, B1); PG8_BAR; PG8_SCHED;
;     ...
;         if constexpr (ALIGN_EPI) { if (wr == 0) PG8_BAR; }
	s_setprio 0
	s_add_i32 s40, s55, s33
	v_lshl_add_u64 v[218:219], v[218:219], 0, s[18:19]
	s_mov_b32 m0, s40
	ds_read_b128 v[184:187], v154 offset:49152
	ds_read_b128 v[188:191], v154 offset:50176
	ds_read_b128 v[192:195], v154 offset:51200
	ds_read_b128 v[196:199], v154 offset:52224
	ds_read_b128 v[200:203], v154 offset:53248
	ds_read_b128 v[204:207], v154 offset:54272
	ds_read_b128 v[208:211], v154 offset:55296
	ds_read_b128 v[212:215], v154 offset:56320
	global_load_lds_dwordx4 v[218:219], off
	s_add_i32 m0, s40, 0x2000
	s_add_u32 s38, s38, 0x400080
	v_lshl_add_u64 v[218:219], v[220:221], 0, s[18:19]
	s_addc_u32 s39, s39, 0
	s_add_i32 s40, s56, s33
	global_load_lds_dwordx4 v[218:219], off
	v_lshl_add_u64 v[218:219], s[38:39], 0, v[132:133]
	s_mov_b32 m0, s40
	s_nop 0
	global_load_lds_dwordx4 v[218:219], off
	v_lshl_add_u64 v[218:219], s[38:39], 0, v[136:137]
	s_add_i32 m0, s40, 0x2000
	s_nop 0
	global_load_lds_dwordx4 v[218:219], off
	v_lshl_add_u64 v[218:219], v[222:223], 0, s[18:19]
	s_mov_b32 m0, s48
	s_nop 0
	global_load_lds_dwordx4 v[218:219], off
	v_lshl_add_u64 v[218:219], v[224:225], 0, s[18:19]
	s_mov_b32 m0, s49
	s_nop 0
	global_load_lds_dwordx4 v[218:219], off
	s_waitcnt vmcnt(8)
	s_waitcnt lgkmcnt(0)
	s_setprio 1
	s_barrier
	v_mfma_f32_16x16x32_bf16 v[62:65], v[146:149], v[184:187], v[62:65]
	v_mfma_f32_16x16x32_bf16 v[58:61], v[160:163], v[184:187], v[58:61]
	v_mfma_f32_16x16x32_bf16 v[46:49], v[146:149], v[192:195], v[46:49]
	v_mfma_f32_16x16x32_bf16 v[42:45], v[160:163], v[192:195], v[42:45]
	v_mfma_f32_16x16x32_bf16 v[30:33], v[146:149], v[200:203], v[30:33]
	v_mfma_f32_16x16x32_bf16 v[26:29], v[160:163], v[200:203], v[26:29]
	v_mfma_f32_16x16x32_bf16 v[14:17], v[146:149], v[208:211], v[14:17]
	v_mfma_f32_16x16x32_bf16 v[10:13], v[160:163], v[208:211], v[10:13]
	v_mfma_f32_16x16x32_bf16 v[62:65], v[156:159], v[188:191], v[62:65]
	v_mfma_f32_16x16x32_bf16 v[58:61], v[164:167], v[188:191], v[58:61]
	v_mfma_f32_16x16x32_bf16 v[46:49], v[156:159], v[196:199], v[46:49]
	v_mfma_f32_16x16x32_bf16 v[42:45], v[164:167], v[196:199], v[42:45]
	v_mfma_f32_16x16x32_bf16 v[30:33], v[156:159], v[204:207], v[30:33]
	v_mfma_f32_16x16x32_bf16 v[26:29], v[164:167], v[204:207], v[26:29]
	v_mfma_f32_16x16x32_bf16 v[14:17], v[156:159], v[212:215], v[14:17]
	v_mfma_f32_16x16x32_bf16 v[10:13], v[164:167], v[212:215], v[10:13]
	s_setprio 0
	s_setprio 1
	v_mfma_f32_16x16x32_bf16 v[54:57], v[168:171], v[184:187], v[54:57]
	v_mfma_f32_16x16x32_bf16 v[50:53], v[176:179], v[184:187], v[50:53]
	v_mfma_f32_16x16x32_bf16 v[38:41], v[168:171], v[192:195], v[38:41]
	v_mfma_f32_16x16x32_bf16 v[34:37], v[176:179], v[192:195], v[34:37]
	v_mfma_f32_16x16x32_bf16 v[22:25], v[168:171], v[200:203], v[22:25]
	v_mfma_f32_16x16x32_bf16 v[18:21], v[176:179], v[200:203], v[18:21]
	v_mfma_f32_16x16x32_bf16 v[6:9], v[168:171], v[208:211], v[6:9]
	v_mfma_f32_16x16x32_bf16 v[2:5], v[176:179], v[208:211], v[2:5]
	v_mfma_f32_16x16x32_bf16 v[54:57], v[172:175], v[188:191], v[54:57]
	v_mfma_f32_16x16x32_bf16 v[50:53], v[180:183], v[188:191], v[50:53]
	v_mfma_f32_16x16x32_bf16 v[38:41], v[172:175], v[196:199], v[38:41]
	v_mfma_f32_16x16x32_bf16 v[34:37], v[180:183], v[196:199], v[34:37]
	v_mfma_f32_16x16x32_bf16 v[22:25], v[172:175], v[204:207], v[22:25]
	v_mfma_f32_16x16x32_bf16 v[18:21], v[180:183], v[204:207], v[18:21]
	v_mfma_f32_16x16x32_bf16 v[6:9], v[172:175], v[212:215], v[6:9]
	v_mfma_f32_16x16x32_bf16 v[2:5], v[180:183], v[212:215], v[2:5]
	s_barrier
	s_setprio 0
	s_add_i32 s54, s54, 2
	s_add_u32 s36, s36, 0x100
	s_addc_u32 s37, s37, 0
	s_add_u32 s52, s52, 0x100
	s_addc_u32 s53, s53, 0
	s_cmpk_gt_u32 s54, 0xfd
	s_cbranch_scc0 .LBB0_1089
	s_and_b64 vcc, exec, s[20:21]
	s_cbranch_vccz .LBB0_1092
	s_barrier
